# tail-round fix for phases 1/5/6/7/8 (sample tiles moved to last round, padding MFMA groups skipped incl. k_rope tile), entry grid.sync removed, attention loop hand-scheduled
# speedup vs baseline: 1.0073x; 1.0073x over previous
; #define LAS __attribute__((address_space(3)))
; __device__ __forceinline__ int my_tid() { int t = threadIdx.x; asm volatile("" : "+v"(t)); return t; }
; __device__ __forceinline__ unsigned xb_add(unsigned* p, unsigned v) { return __hip_atomic_fetch_add(p, v, __ATOMIC_RELAXED, __HIP_MEMORY_SCOPE_AGENT); }
; __device__ __forceinline__ unsigned xb_xcc_id() { return (unsigned)__builtin_amdgcn_s_getreg((3 << 11) | 20) & 0xFu; }
; #define LOAD_PARAMS() KArgs kp_ = (KArgs)__builtin_amdgcn_kernarg_segment_ptr(); asm volatile("" : "+s"(kp_)); const Params P = *kp_; unsigned char* ws = P.ws
; __device__ __forceinline__ void phase0(const Params& P, LAS unsigned char* lds) {
;     ...
;     const int tid = my_tid(), lane = tid & 63, wave = tid >> 6;
;     const int gw = blockIdx.x * 8 + wave, ngw = gridDim.x * 8;
;     const size_t gt = (size_t)blockIdx.x * 512 + tid, ngt = (size_t)gridDim.x * 512;
;     LAS float* scr = (LAS float*)(lds + wave * 16384);
;     for (size_t i = gt; i < (W_SSQ_END - W_SSQ0) / 16; i += ngt) ((u32x4*)(ws + W_SSQ0))[i] = (u32x4){0u, 0u, 0u, 0u};
; __global__ void __launch_bounds__(512, 2) fwd_megakernel(Params Pk) {
;     ...
;     if (threadIdx.x == 0) { xst[0] = 0u; xst[1] = 0u; }
;     __syncthreads();
;     { LOAD_PARAMS(); if (threadIdx.x == 0) (void)xb_add(&((unsigned*)(ws + W_BAR))[XB_XCNT(xb_xcc_id())], 1u); }
;     ...
;     grid.sync();
;     if (PHM & 1) { LOAD_PARAMS(); (void)ws; phase0(P, lds); }
.LBB0_2:
	s_or_b64 exec, exec, s[6:7]
	s_mov_b64 s[10:11], s[86:87]
	s_waitcnt lgkmcnt(0)
	s_barrier
	s_mov_b64 s[6:7], exec
	v_readlane_b32 s0, v255, 1
	v_readlane_b32 s1, v255, 2
	s_and_b64 s[0:1], s[6:7], s[0:1]
	s_mov_b64 exec, s[0:1]
	s_cbranch_execz .LBB0_5
	s_mov_b64 s[12:13], exec
	v_mbcnt_lo_u32_b32 v1, s12, 0
	v_mbcnt_hi_u32_b32 v1, s13, v1
	v_cmp_eq_u32_e32 vcc, 0, v1
	s_getreg_b32 s0, hwreg(HW_REG_XCC_ID, 0, 4)
	s_and_b64 s[4:5], exec, vcc
	s_mov_b64 exec, s[4:5]
	s_cbranch_execz .LBB0_5
	s_load_dwordx2 s[4:5], s[10:11], 0xe8
	s_lshl_b32 s0, s0, 8
	s_and_b32 s0, s0, 0xf00
	v_mov_b32_e32 v1, 0x33d5000
	s_waitcnt lgkmcnt(0)
	s_add_u32 s0, s4, s0
	s_addc_u32 s1, s5, 0
	s_bcnt1_i32_b64 s3, s[12:13]
	v_mov_b32_e32 v2, s3
	global_atomic_add v1, v2, s[0:1] offset:1024
.LBB0_5:
	s_or_b64 exec, exec, s[6:7]
	s_mov_b64 s[0:1], s[86:87]
	s_barrier
	s_load_dwordx8 s[12:19], s[0:1], 0x0
	s_load_dwordx8 s[20:27], s[0:1], 0x30
	s_load_dwordx2 s[58:59], s[0:1], 0x58
	s_load_dwordx2 s[48:49], s[0:1], 0x68
	s_load_dwordx2 s[52:53], s[0:1], 0x80
	s_load_dwordx2 s[54:55], s[0:1], 0x90
	s_load_dwordx2 s[56:57], s[0:1], 0xd8
	s_load_dwordx4 s[28:31], s[0:1], 0xc8
	s_load_dwordx8 s[36:43], s[0:1], 0xa8
	s_load_dwordx2 s[50:51], s[0:1], 0xe8
	v_mov_b32_e32 v82, v230
	s_mov_b32 s3, 0
	s_lshl_b64 s[46:47], s[2:3], 9
	v_ashrrev_i32_e32 v83, 31, v82
	v_lshl_add_u64 v[80:81], s[46:47], 0, v[82:83]
	s_mov_b32 s44, s68
	s_mov_b32 s45, s3
	s_mov_b64 s[0:1], 0x504c0
	s_lshl_b64 s[34:35], s[44:45], 9
	v_cmp_gt_u64_e32 vcc, s[0:1], v[80:81]
	s_and_saveexec_b64 s[6:7], vcc
	s_cbranch_execz .LBB0_18
	s_lshl_b64 s[0:1], s[2:3], 13
	s_waitcnt lgkmcnt(0)
	s_add_u32 s0, s50, s0
	s_addc_u32 s1, s51, s1
	v_lshl_add_u64 v[0:1], v[82:83], 4, s[0:1]
	s_mov_b64 s[0:1], 0x2480000
	v_lshl_add_u64 v[4:5], v[0:1], 0, s[0:1]
	v_mov_b32_e32 v0, 0
	s_lshl_b64 s[8:9], s[44:45], 13
	s_mov_b64 s[10:11], 0
	v_mov_b32_e32 v1, v0
	v_mov_b32_e32 v2, v0
	v_mov_b32_e32 v3, v0
	s_mov_b64 s[60:61], 0x504bf
	v_mov_b64_e32 v[6:7], v[80:81]

;     __device__ __forceinline__ bool next(int i, Unit& u) const {
;         int L = (i / UPT) * G + c;
;         constexpr int n0 = nM0 * nN0, n1 = nM1 * nN1, n2 = nM2 * nN2;
;         if (L < n0) { tile_of(L, nM0, nN0, u.pm, u.pn); u.g = (UPT > 1) ? (i % UPT) : 0; return true; }
;         if constexpr (NG > 1) { L -= n0; if (L < n1) { tile_of(L, nM1, nN1, u.pm, u.pn); u.g = 1; return true; }
.LBB0_248:
	s_add_i32 s92, s92, 1
	s_mul_i32 s51, s92, s68
	s_add_i32 s51, s51, s2
	s_cmpk_lt_i32 s51, 0x1111
	s_cselect_b64 s[66:67], -1, 0
	s_cmpk_gt_i32 s51, 0x1110
	s_cselect_b64 s[48:49], -1, 0
	s_and_b64 vcc, exec, s[48:49]
	s_cbranch_vccnz .LBB0_254
	s_sub_i32 s99, s51, 0x108f
	s_and_b32 s100, s99, 7
	s_cmp_eq_u32 s100, 0
	s_cbranch_scc0 .Lrmp1_a
	s_lshr_b32 s100, s99, 3
	s_cmp_lt_u32 s100, 15
	s_cbranch_scc0 .Lrmp1_a
	s_add_i32 s51, s100, 0x1100
	s_cmp_ge_u32 s100, 7
	s_addc_u32 s51, s51, 0
	s_cmp_ge_u32 s100, 14
	s_addc_u32 s51, s51, 0
	s_branch .Lrmp1_c
.Lrmp1_a:
	s_cmp_lt_i32 s51, 0x1100
	s_cbranch_scc1 .Lrmp1_c
	s_sub_i32 s99, s51, 0x1100
	s_cmp_eq_u32 s99, 7
	s_cbranch_scc1 .Lrmp1_c
	s_cmp_eq_u32 s99, 15
	s_cbranch_scc1 .Lrmp1_c
	s_cmp_gt_u32 s99, 7
	s_cselect_b32 s100, 1, 0
	s_cmp_gt_u32 s99, 15
	s_cselect_b32 s51, 1, 0
	s_sub_i32 s99, s99, s100
	s_sub_i32 s99, s99, s51
	s_lshl_b32 s99, s99, 3
	s_add_i32 s51, s99, 0x108f
.Lrmp1_c:
	s_ashr_i32 s12, s51, 31
	s_lshr_b32 s12, s12, 29
	s_add_i32 s12, s51, s12
	s_and_b32 s50, s12, -8
	s_sub_i32 s52, s51, s50
	s_cmp_gt_i32 s52, 0
	s_mov_b64 s[50:51], -1
	s_cbranch_scc0 .LBB0_251
	s_mul_i32 s50, s52, 0x222
	s_or_b32 s53, s50, 1
	s_mov_b64 s[50:51], 0

; #define PG8_STAGE(bufoff, gbase, voff) do { _Pragma("unroll") for (int _i = 0; _i < 2; ++_i) \
;         __builtin_amdgcn_global_load_lds((const unsigned*)((const char*)(gbase) + (voff)[_i]), (LAS unsigned*)(lds + (bufoff) + ldsw + _i * 8192), 16, 0, 0); } while (0)
; #define PG8_LDA(dst, b, h) do { _Pragma("unroll") for (int m = 0; m < 4; ++m) _Pragma("unroll") for (int k = 0; k < 2; ++k) dst[m][k] = *(const LAS bf16x8*)(lds + PG8_SA(b, h) + aoff + m * 2048 + k * 1024); } while (0)
; #define PG8_LDB(dst, b, h) do { _Pragma("unroll") for (int n = 0; n < 2; ++n) _Pragma("unroll") for (int k = 0; k < 2; ++k) dst[n][k] = *(const LAS bf16x8*)(lds + PG8_SB(b, h) + boff + n * 2048 + k * 1024); } while (0)
; #define PG8_MMA(ai, bj, At, Bt) do { __builtin_amdgcn_s_setprio(1); _Pragma("unroll") for (int m = 0; m < 4; ++m) _Pragma("unroll") for (int n = 0; n < 2; ++n) _Pragma("unroll") for (int k = 0; k < 2; ++k) \
;         acc[ai][bj][m][n] = __builtin_amdgcn_mfma_f32_16x16x32_bf16(Bt[n][k], At[m][k], acc[ai][bj][m][n], 0, 0, 0); __builtin_amdgcn_s_setprio(0); } while (0)
; #define PG8_WAIT_L(n) asm volatile("s_waitcnt lgkmcnt(" #n ")" ::: "memory")
; #define PG8_BAR __builtin_amdgcn_s_barrier()
; #define PG8_SCHED __builtin_amdgcn_sched_barrier(0)
; template <class Epi, class Sched>
; __device__ __forceinline__ void gemm_phase(LAS unsigned char* lds, const int K, const Sched& S, const Epi& E) {
;     ...
;         for (int t = 0; t < nt; t += 2) {
;             const bool last = (t == nt - 2);
;             const char* a1 = cA + (size_t)(t + 1) * kstep;
;             const char* a2 = last ? nA : cA + (size_t)(t + 2) * kstep; const char* b2 = last ? nB : cB + (size_t)(t + 2) * kstep;
;             const char* a3 = a2 + kstep; const char* b3 = b2 + kstep;
;             PG8_LDB(B0, 0, 0); PG8_SCHED; PG8_LDA(At, 0, 0); PG8_STAGE(PG8_SA(1, 1), a1 + hstep, voffA);
;             PG8_WAIT_L(8); PG8_BAR; PG8_WAIT_L(0); PG8_MMA(0, 0, At, B0); PG8_BAR; PG8_SCHED;
;     ...
;         for (int a = 0; a < 2; ++a)
; #pragma unroll
;             for (int b = 0; b < 2; ++b)
; #pragma unroll
;                 for (int m = 0; m < 4; ++m)
; #pragma unroll
;                     for (int n = 0; n < 2; ++n) acc[a][b][m][n] = (f32x4){0.f, 0.f, 0.f, 0.f};
;         cur = nxt; cA = nA; cB = nB; ++ui;
.LBB0_254:
	s_ashr_i32 s53, s52, 31
	s_lshl_b64 s[54:55], s[52:53], 19
	s_add_u32 s54, s33, s54
	s_addc_u32 s55, s70, s55
	s_and_b64 s[56:57], s[66:67], exec
	s_cselect_b32 s12, s55, s63
	s_cselect_b32 s53, s54, s62
	s_ashr_i32 s51, s50, 31
	s_lshl_b64 s[56:57], s[50:51], 19
	s_add_u32 s56, s10, s56
	s_addc_u32 s57, s11, s57
	s_and_b64 s[66:67], s[66:67], exec
	s_cselect_b32 s51, s57, s65
	s_cselect_b32 s59, s56, s64
	s_add_u32 s62, s62, 0x40080
	s_addc_u32 s63, s63, 0
	s_add_u32 s61, s64, 0x100
	v_mov_b32_e32 v0, 0
	s_addc_u32 s93, s65, 0
	s_mov_b32 s94, -2
	v_mov_b32_e32 v1, v0
	v_mov_b32_e32 v2, v0
	v_mov_b32_e32 v3, v0
	v_mov_b32_e32 v4, v0
	s_waitcnt lgkmcnt(0)
	v_mov_b32_e32 v5, v0
	v_mov_b32_e32 v6, v0
	v_mov_b32_e32 v7, v0
	v_mov_b32_e32 v16, v0
	v_mov_b32_e32 v17, v0
	v_mov_b32_e32 v18, v0
	v_mov_b32_e32 v19, v0
	v_mov_b32_e32 v20, v0
	v_mov_b32_e32 v21, v0
	v_mov_b32_e32 v22, v0
	v_mov_b32_e32 v23, v0
	v_mov_b32_e32 v32, v0
	v_mov_b32_e32 v33, v0
	v_mov_b32_e32 v34, v0
	v_mov_b32_e32 v35, v0
	v_mov_b32_e32 v36, v0
	v_mov_b32_e32 v37, v0
	v_mov_b32_e32 v38, v0
	v_mov_b32_e32 v39, v0
	v_mov_b32_e32 v48, v0
	v_mov_b32_e32 v49, v0
	v_mov_b32_e32 v50, v0
	v_mov_b32_e32 v51, v0
	v_mov_b32_e32 v52, v0
	v_mov_b32_e32 v53, v0
	v_mov_b32_e32 v54, v0
	v_mov_b32_e32 v55, v0
	v_mov_b32_e32 v8, v0
	v_mov_b32_e32 v9, v0
	v_mov_b32_e32 v10, v0
	v_mov_b32_e32 v11, v0
	v_mov_b32_e32 v12, v0
	v_mov_b32_e32 v13, v0
	v_mov_b32_e32 v14, v0
	v_mov_b32_e32 v15, v0
	v_mov_b32_e32 v24, v0
	v_mov_b32_e32 v25, v0
	v_mov_b32_e32 v26, v0
	v_mov_b32_e32 v27, v0
	v_mov_b32_e32 v28, v0
	v_mov_b32_e32 v29, v0
	v_mov_b32_e32 v30, v0
	v_mov_b32_e32 v31, v0
	v_mov_b32_e32 v40, v0
	v_mov_b32_e32 v41, v0
	v_mov_b32_e32 v42, v0
	v_mov_b32_e32 v43, v0
	v_mov_b32_e32 v44, v0
	v_mov_b32_e32 v45, v0
	v_mov_b32_e32 v46, v0
	v_mov_b32_e32 v47, v0
	v_mov_b32_e32 v56, v0
	v_mov_b32_e32 v57, v0
	v_mov_b32_e32 v58, v0
	v_mov_b32_e32 v59, v0
	v_mov_b32_e32 v60, v0
	v_mov_b32_e32 v61, v0
	v_mov_b32_e32 v62, v0
	v_mov_b32_e32 v63, v0
	v_mov_b32_e32 v64, v0
	v_mov_b32_e32 v65, v0
	v_mov_b32_e32 v66, v0
	v_mov_b32_e32 v67, v0
	v_mov_b32_e32 v68, v0
	v_mov_b32_e32 v69, v0
	v_mov_b32_e32 v70, v0
	v_mov_b32_e32 v71, v0
	v_mov_b32_e32 v80, v0
	v_mov_b32_e32 v81, v0
	v_mov_b32_e32 v82, v0
	v_mov_b32_e32 v83, v0
	v_mov_b32_e32 v84, v0
	v_mov_b32_e32 v85, v0
	v_mov_b32_e32 v86, v0
	v_mov_b32_e32 v87, v0
	v_mov_b32_e32 v96, v0
	v_mov_b32_e32 v97, v0
	v_mov_b32_e32 v98, v0
	v_mov_b32_e32 v99, v0
	v_mov_b32_e32 v100, v0
	v_mov_b32_e32 v101, v0
	v_mov_b32_e32 v102, v0
	v_mov_b32_e32 v103, v0
	v_mov_b32_e32 v112, v0
	v_mov_b32_e32 v113, v0
	v_mov_b32_e32 v114, v0
	v_mov_b32_e32 v115, v0
	v_mov_b32_e32 v116, v0
	v_mov_b32_e32 v117, v0
	v_mov_b32_e32 v118, v0
	v_mov_b32_e32 v119, v0
	v_mov_b32_e32 v72, v0
	v_mov_b32_e32 v73, v0
	v_mov_b32_e32 v74, v0
	v_mov_b32_e32 v75, v0
	v_mov_b32_e32 v76, v0
	v_mov_b32_e32 v77, v0
	v_mov_b32_e32 v78, v0
	v_mov_b32_e32 v79, v0
	v_mov_b32_e32 v88, v0
	v_mov_b32_e32 v89, v0
	v_mov_b32_e32 v90, v0
	v_mov_b32_e32 v91, v0
	v_mov_b32_e32 v92, v0
	v_mov_b32_e32 v93, v0
	v_mov_b32_e32 v94, v0
	v_mov_b32_e32 v95, v0
	v_mov_b32_e32 v104, v0
	v_mov_b32_e32 v105, v0
	v_mov_b32_e32 v106, v0
	v_mov_b32_e32 v107, v0
	v_mov_b32_e32 v108, v0
	v_mov_b32_e32 v109, v0
	v_mov_b32_e32 v110, v0
	v_mov_b32_e32 v111, v0
	v_mov_b32_e32 v120, v0
	v_mov_b32_e32 v121, v0
	v_mov_b32_e32 v122, v0
	v_mov_b32_e32 v123, v0
	v_mov_b32_e32 v124, v0
	v_mov_b32_e32 v125, v0
	v_mov_b32_e32 v126, v0
	v_mov_b32_e32 v127, v0
	s_cmpk_eq_i32 s58, 0x10
	s_cselect_b32 s101, 1, 0
	s_cmpk_eq_i32 s60, 0x100
	s_cselect_b32 s100, 2, 0
	s_or_b32 s101, s101, s100
.LBB0_255:
	ds_read_b128 v[146:149], v153
	ds_read_b128 v[160:163], v153 offset:1024
	ds_read_b128 v[164:167], v153 offset:2048
	ds_read_b128 v[168:171], v153 offset:3072
	s_add_u32 s64, s62, 0xfffc0080
	s_addc_u32 s65, s63, -1
	s_cmp_eq_u32 s94, 12
	s_cselect_b32 s67, s12, s65
	s_cselect_b32 s66, s53, s64
	s_cselect_b32 s65, s51, s93
	s_cselect_b32 s64, s59, s61
	v_lshl_add_u64 v[150:151], s[62:63], 0, v[142:143]
	s_add_i32 m0, s5, 0xc000
	ds_read_b128 v[172:175], v154
	ds_read_b128 v[176:179], v154 offset:1024
	ds_read_b128 v[180:183], v154 offset:2048
	ds_read_b128 v[184:187], v154 offset:3072
	ds_read_b128 v[188:191], v154 offset:4096
	ds_read_b128 v[192:195], v154 offset:5120
	ds_read_b128 v[196:199], v154 offset:6144
	ds_read_b128 v[200:203], v154 offset:7168
	global_load_lds_dwordx4 v[150:151], off
	v_lshl_add_u64 v[150:151], s[62:63], 0, v[144:145]
	s_add_i32 m0, s5, 0xe000
	s_nop 0
	global_load_lds_dwordx4 v[150:151], off
	s_waitcnt lgkmcnt(8)
	s_barrier
	s_waitcnt lgkmcnt(0)
	s_setprio 1
	s_waitcnt lgkmcnt(0)
	v_mfma_f32_16x16x32_bf16 v[124:127], v[146:149], v[172:175], v[124:127]
	v_mfma_f32_16x16x32_bf16 v[120:123], v[164:167], v[172:175], v[120:123]
	v_mfma_f32_16x16x32_bf16 v[108:111], v[146:149], v[180:183], v[108:111]
	v_mfma_f32_16x16x32_bf16 v[104:107], v[164:167], v[180:183], v[104:107]
	v_mfma_f32_16x16x32_bf16 v[92:95], v[146:149], v[188:191], v[92:95]
	v_mfma_f32_16x16x32_bf16 v[88:91], v[164:167], v[188:191], v[88:91]
	v_mfma_f32_16x16x32_bf16 v[76:79], v[146:149], v[196:199], v[76:79]
	v_mfma_f32_16x16x32_bf16 v[72:75], v[164:167], v[196:199], v[72:75]
	v_mfma_f32_16x16x32_bf16 v[124:127], v[160:163], v[176:179], v[124:127]
	v_mfma_f32_16x16x32_bf16 v[120:123], v[168:171], v[176:179], v[120:123]
	v_mfma_f32_16x16x32_bf16 v[108:111], v[160:163], v[184:187], v[108:111]
	v_mfma_f32_16x16x32_bf16 v[104:107], v[168:171], v[184:187], v[104:107]
	v_mfma_f32_16x16x32_bf16 v[92:95], v[160:163], v[192:195], v[92:95]
	v_mfma_f32_16x16x32_bf16 v[88:91], v[168:171], v[192:195], v[88:91]
	v_mfma_f32_16x16x32_bf16 v[76:79], v[160:163], v[200:203], v[76:79]
	v_mfma_f32_16x16x32_bf16 v[72:75], v[168:171], v[200:203], v[72:75]
	s_setprio 0
	s_barrier
; #define PG8_STAGE(bufoff, gbase, voff) do { _Pragma("unroll") for (int _i = 0; _i < 2; ++_i) \
;         __builtin_amdgcn_global_load_lds((const unsigned*)((const char*)(gbase) + (voff)[_i]), (LAS unsigned*)(lds + (bufoff) + ldsw + _i * 8192), 16, 0, 0); } while (0)
; #define PG8_LDA(dst, b, h) do { _Pragma("unroll") for (int m = 0; m < 4; ++m) _Pragma("unroll") for (int k = 0; k < 2; ++k) dst[m][k] = *(const LAS bf16x8*)(lds + PG8_SA(b, h) + aoff + m * 2048 + k * 1024); } while (0)
; #define PG8_LDB(dst, b, h) do { _Pragma("unroll") for (int n = 0; n < 2; ++n) _Pragma("unroll") for (int k = 0; k < 2; ++k) dst[n][k] = *(const LAS bf16x8*)(lds + PG8_SB(b, h) + boff + n * 2048 + k * 1024); } while (0)
; #define PG8_MMA(ai, bj, At, Bt) do { __builtin_amdgcn_s_setprio(1); _Pragma("unroll") for (int m = 0; m < 4; ++m) _Pragma("unroll") for (int n = 0; n < 2; ++n) _Pragma("unroll") for (int k = 0; k < 2; ++k) \
;         acc[ai][bj][m][n] = __builtin_amdgcn_mfma_f32_16x16x32_bf16(Bt[n][k], At[m][k], acc[ai][bj][m][n], 0, 0, 0); __builtin_amdgcn_s_setprio(0); } while (0)
; #define PG8_WAIT_V(n) asm volatile("s_waitcnt vmcnt(" #n ")" ::: "memory")
; #define PG8_WAIT_L(n) asm volatile("s_waitcnt lgkmcnt(" #n ")" ::: "memory")
; #define PG8_BAR __builtin_amdgcn_s_barrier()
; #define PG8_SCHED __builtin_amdgcn_sched_barrier(0)
; template <class Epi, class Sched>
; __device__ __forceinline__ void gemm_phase(LAS unsigned char* lds, const int K, const Sched& S, const Epi& E) {
;     ...
;             PG8_WAIT_L(8); PG8_BAR; PG8_WAIT_L(0); PG8_MMA(0, 0, At, B0); PG8_BAR; PG8_SCHED;
;             PG8_LDB(B1, 0, 1); PG8_STAGE(PG8_SB(0, 0), b2, voffB);
;             PG8_BAR; PG8_WAIT_L(0); PG8_MMA(0, 1, At, B1); PG8_BAR;
;             PG8_LDA(At, 0, 1); PG8_STAGE(PG8_SA(0, 0), a2, voffA);
;             PG8_BAR; PG8_WAIT_L(0); PG8_MMA(1, 0, At, B0); PG8_BAR; PG8_SCHED;
;             PG8_STAGE(PG8_SB(0, 1), b2 + hstep, voffB);
;             PG8_WAIT_V(6); PG8_BAR; PG8_MMA(1, 1, At, B1); PG8_BAR;
	s_add_i32 s95, s79, s4
	v_lshl_add_u64 v[150:151], s[64:65], 0, v[130:131]
	s_mov_b32 m0, s95
	ds_read_b128 v[204:207], v155
	ds_read_b128 v[208:211], v155 offset:1024
	ds_read_b128 v[212:215], v155 offset:2048
	ds_read_b128 v[216:219], v155 offset:3072
	global_load_lds_dwordx4 v[150:151], off
	v_lshl_add_u64 v[220:221], s[64:65], 0, v[134:135]
	s_add_i32 m0, s95, 0x2000
	s_nop 0
	global_load_lds_dwordx4 v[220:221], off
	s_barrier
	s_waitcnt lgkmcnt(0)
	s_bitcmp1_b32 s101, 0
	s_cbranch_scc1 .Lskp1_1
	s_setprio 1
	s_waitcnt lgkmcnt(0)
	v_mfma_f32_16x16x32_bf16 v[116:119], v[204:207], v[172:175], v[116:119]
	v_mfma_f32_16x16x32_bf16 v[112:115], v[212:215], v[172:175], v[112:115]
	v_mfma_f32_16x16x32_bf16 v[100:103], v[204:207], v[180:183], v[100:103]
	v_mfma_f32_16x16x32_bf16 v[96:99], v[212:215], v[180:183], v[96:99]
	v_mfma_f32_16x16x32_bf16 v[84:87], v[204:207], v[188:191], v[84:87]
	v_mfma_f32_16x16x32_bf16 v[80:83], v[212:215], v[188:191], v[80:83]
	v_mfma_f32_16x16x32_bf16 v[68:71], v[204:207], v[196:199], v[68:71]
	v_mfma_f32_16x16x32_bf16 v[64:67], v[212:215], v[196:199], v[64:67]
	v_mfma_f32_16x16x32_bf16 v[116:119], v[208:211], v[176:179], v[116:119]
	v_mfma_f32_16x16x32_bf16 v[112:115], v[216:219], v[176:179], v[112:115]
	v_mfma_f32_16x16x32_bf16 v[100:103], v[208:211], v[184:187], v[100:103]
	v_mfma_f32_16x16x32_bf16 v[96:99], v[216:219], v[184:187], v[96:99]
	v_mfma_f32_16x16x32_bf16 v[84:87], v[208:211], v[192:195], v[84:87]
	v_mfma_f32_16x16x32_bf16 v[80:83], v[216:219], v[192:195], v[80:83]
	v_mfma_f32_16x16x32_bf16 v[68:71], v[208:211], v[200:203], v[68:71]
	v_mfma_f32_16x16x32_bf16 v[64:67], v[216:219], v[200:203], v[64:67]
	s_setprio 0
.Lskp1_1:
	s_mov_b32 m0, s5
	v_lshl_add_u64 v[222:223], s[66:67], 0, v[128:129]
	s_barrier
	ds_read_b128 v[172:175], v154 offset:16384
	ds_read_b128 v[176:179], v154 offset:17408
	ds_read_b128 v[180:183], v154 offset:18432
	ds_read_b128 v[184:187], v154 offset:19456
	ds_read_b128 v[188:191], v154 offset:20480
	ds_read_b128 v[192:195], v154 offset:21504
	ds_read_b128 v[196:199], v154 offset:22528
	ds_read_b128 v[200:203], v154 offset:23552
	global_load_lds_dwordx4 v[222:223], off
	v_lshl_add_u64 v[224:225], s[66:67], 0, v[132:133]
	s_mov_b32 m0, s71
	s_nop 0
	global_load_lds_dwordx4 v[224:225], off
	s_barrier
	s_waitcnt lgkmcnt(0)
	s_bitcmp1_b32 s101, 1
	s_cbranch_scc1 .Lskp1_2
	s_setprio 1
	s_waitcnt lgkmcnt(0)
	v_mfma_f32_16x16x32_bf16 v[60:63], v[146:149], v[172:175], v[60:63]
	v_mfma_f32_16x16x32_bf16 v[56:59], v[164:167], v[172:175], v[56:59]
	v_mfma_f32_16x16x32_bf16 v[44:47], v[146:149], v[180:183], v[44:47]
	v_mfma_f32_16x16x32_bf16 v[40:43], v[164:167], v[180:183], v[40:43]
	v_mfma_f32_16x16x32_bf16 v[28:31], v[146:149], v[188:191], v[28:31]
	v_mfma_f32_16x16x32_bf16 v[24:27], v[164:167], v[188:191], v[24:27]
	v_mfma_f32_16x16x32_bf16 v[12:15], v[146:149], v[196:199], v[12:15]
	v_mfma_f32_16x16x32_bf16 v[8:11], v[164:167], v[196:199], v[8:11]
	v_mfma_f32_16x16x32_bf16 v[60:63], v[160:163], v[176:179], v[60:63]
	v_mfma_f32_16x16x32_bf16 v[56:59], v[168:171], v[176:179], v[56:59]
	v_mfma_f32_16x16x32_bf16 v[44:47], v[160:163], v[184:187], v[44:47]
	v_mfma_f32_16x16x32_bf16 v[40:43], v[168:171], v[184:187], v[40:43]
	v_mfma_f32_16x16x32_bf16 v[28:31], v[160:163], v[192:195], v[28:31]
	v_mfma_f32_16x16x32_bf16 v[24:27], v[168:171], v[192:195], v[24:27]
	v_mfma_f32_16x16x32_bf16 v[12:15], v[160:163], v[200:203], v[12:15]
	v_mfma_f32_16x16x32_bf16 v[8:11], v[168:171], v[200:203], v[8:11]
	s_setprio 0
.Lskp1_2:
	s_barrier
	s_add_u32 s96, s64, 0x40000
	s_addc_u32 s97, s65, 0
	s_add_i32 s95, s80, s4
	v_lshl_add_u64 v[146:147], s[96:97], 0, v[130:131]
	s_mov_b32 m0, s95
	s_nop 0
	global_load_lds_dwordx4 v[146:147], off
	v_lshl_add_u64 v[146:147], s[96:97], 0, v[134:135]
	s_add_i32 m0, s95, 0x2000
	s_nop 0
	global_load_lds_dwordx4 v[146:147], off
	s_waitcnt vmcnt(6)
	s_barrier
	s_cmp_lg_u32 s101, 0
	s_cbranch_scc1 .Lskp1_3
	s_setprio 1
	v_mfma_f32_16x16x32_bf16 v[52:55], v[204:207], v[172:175], v[52:55]
	v_mfma_f32_16x16x32_bf16 v[48:51], v[212:215], v[172:175], v[48:51]
	v_mfma_f32_16x16x32_bf16 v[36:39], v[204:207], v[180:183], v[36:39]
	v_mfma_f32_16x16x32_bf16 v[32:35], v[212:215], v[180:183], v[32:35]
	v_mfma_f32_16x16x32_bf16 v[20:23], v[204:207], v[188:191], v[20:23]
	v_mfma_f32_16x16x32_bf16 v[16:19], v[212:215], v[188:191], v[16:19]
	v_mfma_f32_16x16x32_bf16 v[4:7], v[204:207], v[196:199], v[4:7]
	v_mfma_f32_16x16x32_bf16 v[0:3], v[212:215], v[196:199], v[0:3]
	v_mfma_f32_16x16x32_bf16 v[52:55], v[208:211], v[176:179], v[52:55]
	v_mfma_f32_16x16x32_bf16 v[48:51], v[216:219], v[176:179], v[48:51]
	v_mfma_f32_16x16x32_bf16 v[36:39], v[208:211], v[184:187], v[36:39]
	v_mfma_f32_16x16x32_bf16 v[32:35], v[216:219], v[184:187], v[32:35]
	v_mfma_f32_16x16x32_bf16 v[20:23], v[208:211], v[192:195], v[20:23]
	v_mfma_f32_16x16x32_bf16 v[16:19], v[216:219], v[192:195], v[16:19]
	v_mfma_f32_16x16x32_bf16 v[4:7], v[208:211], v[200:203], v[4:7]
	v_mfma_f32_16x16x32_bf16 v[0:3], v[216:219], v[200:203], v[0:3]
	s_setprio 0
; #define PG8_STAGE(bufoff, gbase, voff) do { _Pragma("unroll") for (int _i = 0; _i < 2; ++_i) \
;         __builtin_amdgcn_global_load_lds((const unsigned*)((const char*)(gbase) + (voff)[_i]), (LAS unsigned*)(lds + (bufoff) + ldsw + _i * 8192), 16, 0, 0); } while (0)
; #define PG8_LDA(dst, b, h) do { _Pragma("unroll") for (int m = 0; m < 4; ++m) _Pragma("unroll") for (int k = 0; k < 2; ++k) dst[m][k] = *(const LAS bf16x8*)(lds + PG8_SA(b, h) + aoff + m * 2048 + k * 1024); } while (0)
; #define PG8_LDB(dst, b, h) do { _Pragma("unroll") for (int n = 0; n < 2; ++n) _Pragma("unroll") for (int k = 0; k < 2; ++k) dst[n][k] = *(const LAS bf16x8*)(lds + PG8_SB(b, h) + boff + n * 2048 + k * 1024); } while (0)
; #define PG8_MMA(ai, bj, At, Bt) do { __builtin_amdgcn_s_setprio(1); _Pragma("unroll") for (int m = 0; m < 4; ++m) _Pragma("unroll") for (int n = 0; n < 2; ++n) _Pragma("unroll") for (int k = 0; k < 2; ++k) \
;         acc[ai][bj][m][n] = __builtin_amdgcn_mfma_f32_16x16x32_bf16(Bt[n][k], At[m][k], acc[ai][bj][m][n], 0, 0, 0); __builtin_amdgcn_s_setprio(0); } while (0)
; #define PG8_WAIT_L(n) asm volatile("s_waitcnt lgkmcnt(" #n ")" ::: "memory")
; #define PG8_BAR __builtin_amdgcn_s_barrier()
; #define PG8_SCHED __builtin_amdgcn_sched_barrier(0)
; template <class Epi, class Sched>
; __device__ __forceinline__ void gemm_phase(LAS unsigned char* lds, const int K, const Sched& S, const Epi& E) {
;     ...
;             PG8_LDB(B0, 1, 0); PG8_SCHED; PG8_LDA(At, 1, 0); PG8_STAGE(PG8_SA(0, 1), a2 + hstep, voffA);
;             PG8_WAIT_L(8); PG8_BAR; PG8_WAIT_L(0); PG8_MMA(0, 0, At, B0); PG8_BAR; PG8_SCHED;
;             PG8_LDB(B1, 1, 1); PG8_STAGE(PG8_SB(1, 0), b3, voffB);
;             PG8_BAR; PG8_WAIT_L(0); PG8_MMA(0, 1, At, B1); PG8_BAR;
.Lskp1_3:
	s_add_i32 s95, 0, 0x18000
	v_add_u32_e32 v136, s95, v152
	s_barrier
	ds_read_b128 v[146:149], v136
	ds_read_b128 v[160:163], v136 offset:1024
	ds_read_b128 v[164:167], v136 offset:2048
	ds_read_b128 v[168:171], v136 offset:3072
	s_add_u32 s66, s66, 0x40000
	s_addc_u32 s67, s67, 0
	s_mov_b32 m0, s72
	v_lshl_add_u64 v[204:205], s[66:67], 0, v[128:129]
	ds_read_b128 v[172:175], v154 offset:32768
	ds_read_b128 v[176:179], v154 offset:33792
	ds_read_b128 v[180:183], v154 offset:34816
	ds_read_b128 v[184:187], v154 offset:35840
	ds_read_b128 v[188:191], v154 offset:36864
	ds_read_b128 v[192:195], v154 offset:37888
	ds_read_b128 v[196:199], v154 offset:38912
	ds_read_b128 v[200:203], v154 offset:39936
	global_load_lds_dwordx4 v[204:205], off
	v_lshl_add_u64 v[204:205], s[66:67], 0, v[132:133]
	s_mov_b32 m0, s73
	s_nop 0
	global_load_lds_dwordx4 v[204:205], off
	s_waitcnt lgkmcnt(8)
	s_barrier
	s_waitcnt lgkmcnt(0)
	s_setprio 1
	s_waitcnt lgkmcnt(0)
	v_mfma_f32_16x16x32_bf16 v[124:127], v[146:149], v[172:175], v[124:127]
	v_mfma_f32_16x16x32_bf16 v[120:123], v[164:167], v[172:175], v[120:123]
	v_mfma_f32_16x16x32_bf16 v[108:111], v[146:149], v[180:183], v[108:111]
	v_mfma_f32_16x16x32_bf16 v[104:107], v[164:167], v[180:183], v[104:107]
	v_mfma_f32_16x16x32_bf16 v[92:95], v[146:149], v[188:191], v[92:95]
	v_mfma_f32_16x16x32_bf16 v[88:91], v[164:167], v[188:191], v[88:91]
	v_mfma_f32_16x16x32_bf16 v[76:79], v[146:149], v[196:199], v[76:79]
	v_mfma_f32_16x16x32_bf16 v[72:75], v[164:167], v[196:199], v[72:75]
	v_mfma_f32_16x16x32_bf16 v[124:127], v[160:163], v[176:179], v[124:127]
	v_mfma_f32_16x16x32_bf16 v[120:123], v[168:171], v[176:179], v[120:123]
	v_mfma_f32_16x16x32_bf16 v[108:111], v[160:163], v[184:187], v[108:111]
	v_mfma_f32_16x16x32_bf16 v[104:107], v[168:171], v[184:187], v[104:107]
	v_mfma_f32_16x16x32_bf16 v[92:95], v[160:163], v[192:195], v[92:95]
	v_mfma_f32_16x16x32_bf16 v[88:91], v[168:171], v[192:195], v[88:91]
	v_mfma_f32_16x16x32_bf16 v[76:79], v[160:163], v[200:203], v[76:79]
	v_mfma_f32_16x16x32_bf16 v[72:75], v[168:171], v[200:203], v[72:75]
	s_setprio 0
	s_barrier
	s_add_i32 s66, 0, 0x1c000
	s_add_i32 s67, s95, s4
	v_add_u32_e32 v136, s66, v152
	v_lshl_add_u64 v[150:151], v[150:151], 0, s[14:15]
	s_mov_b32 m0, s67
	ds_read_b128 v[204:207], v136
	ds_read_b128 v[208:211], v136 offset:1024
	ds_read_b128 v[212:215], v136 offset:2048
	ds_read_b128 v[216:219], v136 offset:3072
	global_load_lds_dwordx4 v[150:151], off
	v_lshl_add_u64 v[150:151], v[220:221], 0, s[14:15]
	s_add_i32 m0, s67, 0x2000
	s_nop 0
	global_load_lds_dwordx4 v[150:151], off
	s_barrier
	s_waitcnt lgkmcnt(0)
	s_bitcmp1_b32 s101, 0
	s_cbranch_scc1 .Lskp1_5
	s_setprio 1
	s_waitcnt lgkmcnt(0)
	v_mfma_f32_16x16x32_bf16 v[116:119], v[204:207], v[172:175], v[116:119]
	v_mfma_f32_16x16x32_bf16 v[112:115], v[212:215], v[172:175], v[112:115]
	v_mfma_f32_16x16x32_bf16 v[100:103], v[204:207], v[180:183], v[100:103]
	v_mfma_f32_16x16x32_bf16 v[96:99], v[212:215], v[180:183], v[96:99]
	v_mfma_f32_16x16x32_bf16 v[84:87], v[204:207], v[188:191], v[84:87]
	v_mfma_f32_16x16x32_bf16 v[80:83], v[212:215], v[188:191], v[80:83]
	v_mfma_f32_16x16x32_bf16 v[68:71], v[204:207], v[196:199], v[68:71]
	v_mfma_f32_16x16x32_bf16 v[64:67], v[212:215], v[196:199], v[64:67]
	v_mfma_f32_16x16x32_bf16 v[116:119], v[208:211], v[176:179], v[116:119]
	v_mfma_f32_16x16x32_bf16 v[112:115], v[216:219], v[176:179], v[112:115]
	v_mfma_f32_16x16x32_bf16 v[100:103], v[208:211], v[184:187], v[100:103]
	v_mfma_f32_16x16x32_bf16 v[96:99], v[216:219], v[184:187], v[96:99]
	v_mfma_f32_16x16x32_bf16 v[84:87], v[208:211], v[192:195], v[84:87]
	v_mfma_f32_16x16x32_bf16 v[80:83], v[216:219], v[192:195], v[80:83]
	v_mfma_f32_16x16x32_bf16 v[68:71], v[208:211], v[200:203], v[68:71]
	v_mfma_f32_16x16x32_bf16 v[64:67], v[216:219], v[200:203], v[64:67]
	s_setprio 0
; #define PG8_STAGE(bufoff, gbase, voff) do { _Pragma("unroll") for (int _i = 0; _i < 2; ++_i) \
;         __builtin_amdgcn_global_load_lds((const unsigned*)((const char*)(gbase) + (voff)[_i]), (LAS unsigned*)(lds + (bufoff) + ldsw + _i * 8192), 16, 0, 0); } while (0)
; #define PG8_LDA(dst, b, h) do { _Pragma("unroll") for (int m = 0; m < 4; ++m) _Pragma("unroll") for (int k = 0; k < 2; ++k) dst[m][k] = *(const LAS bf16x8*)(lds + PG8_SA(b, h) + aoff + m * 2048 + k * 1024); } while (0)
; #define PG8_MMA(ai, bj, At, Bt) do { __builtin_amdgcn_s_setprio(1); _Pragma("unroll") for (int m = 0; m < 4; ++m) _Pragma("unroll") for (int n = 0; n < 2; ++n) _Pragma("unroll") for (int k = 0; k < 2; ++k) \
;         acc[ai][bj][m][n] = __builtin_amdgcn_mfma_f32_16x16x32_bf16(Bt[n][k], At[m][k], acc[ai][bj][m][n], 0, 0, 0); __builtin_amdgcn_s_setprio(0); } while (0)
; #define PG8_WAIT_V(n) asm volatile("s_waitcnt vmcnt(" #n ")" ::: "memory")
; #define PG8_WAIT_L(n) asm volatile("s_waitcnt lgkmcnt(" #n ")" ::: "memory")
; #define PG8_BAR __builtin_amdgcn_s_barrier()
; #define PG8_SCHED __builtin_amdgcn_sched_barrier(0)
; template <class Epi, class Sched>
; __device__ __forceinline__ void gemm_phase(LAS unsigned char* lds, const int K, const Sched& S, const Epi& E) {
;     ...
;             PG8_LDA(At, 1, 1); PG8_STAGE(PG8_SA(1, 0), a3, voffA);
;             PG8_BAR; PG8_WAIT_L(0); PG8_MMA(1, 0, At, B0); PG8_BAR; PG8_SCHED;
;             PG8_STAGE(PG8_SB(1, 1), b3 + hstep, voffB);
;             PG8_WAIT_V(6); PG8_BAR; PG8_MMA(1, 1, At, B1); PG8_BAR;
;     __device__ __forceinline__ void operator()(Acc& acc, const Unit& u, int wr, int wc, int fr, int fq) const {
;     ...
;                 if (wc < 2) {
; #pragma unroll
;                     for (int ai = 0; ai < 2; ++ai)
; #pragma unroll
;                         for (int m = 0; m < 4; ++m) { const int R = row0 + ai * 128 + m * 16;
;                             if (R < MP + MS) { float* d = (R < MP ? P.out + O_KRP + (size_t)R * 64 : P.out + O_KRS + (size_t)(R - MP) * 64) + cl0; *(f32x4*)d = acc[ai][0][m][0]; *(f32x4*)(d + 4) = acc[ai][0][m][1]; } }
.Lskp1_5:
	s_mov_b32 m0, s77
	v_lshl_add_u64 v[150:151], v[222:223], 0, s[14:15]
	s_barrier
	ds_read_b128 v[172:175], v154 offset:49152
	ds_read_b128 v[176:179], v154 offset:50176
	ds_read_b128 v[180:183], v154 offset:51200
	ds_read_b128 v[184:187], v154 offset:52224
	ds_read_b128 v[188:191], v154 offset:53248
	ds_read_b128 v[192:195], v154 offset:54272
	ds_read_b128 v[196:199], v154 offset:55296
	ds_read_b128 v[200:203], v154 offset:56320
	global_load_lds_dwordx4 v[150:151], off
	v_lshl_add_u64 v[150:151], v[224:225], 0, s[14:15]
	s_mov_b32 m0, s78
	s_nop 0
	global_load_lds_dwordx4 v[150:151], off
	s_barrier
	s_waitcnt lgkmcnt(0)
	s_bitcmp1_b32 s101, 1
	s_cbranch_scc1 .Lskp1_6
	s_setprio 1
	s_waitcnt lgkmcnt(0)
	v_mfma_f32_16x16x32_bf16 v[60:63], v[146:149], v[172:175], v[60:63]
	v_mfma_f32_16x16x32_bf16 v[56:59], v[164:167], v[172:175], v[56:59]
	v_mfma_f32_16x16x32_bf16 v[44:47], v[146:149], v[180:183], v[44:47]
	v_mfma_f32_16x16x32_bf16 v[40:43], v[164:167], v[180:183], v[40:43]
	v_mfma_f32_16x16x32_bf16 v[28:31], v[146:149], v[188:191], v[28:31]
	v_mfma_f32_16x16x32_bf16 v[24:27], v[164:167], v[188:191], v[24:27]
	v_mfma_f32_16x16x32_bf16 v[12:15], v[146:149], v[196:199], v[12:15]
	v_mfma_f32_16x16x32_bf16 v[8:11], v[164:167], v[196:199], v[8:11]
	v_mfma_f32_16x16x32_bf16 v[60:63], v[160:163], v[176:179], v[60:63]
	v_mfma_f32_16x16x32_bf16 v[56:59], v[168:171], v[176:179], v[56:59]
	v_mfma_f32_16x16x32_bf16 v[44:47], v[160:163], v[184:187], v[44:47]
	v_mfma_f32_16x16x32_bf16 v[40:43], v[168:171], v[184:187], v[40:43]
	v_mfma_f32_16x16x32_bf16 v[28:31], v[160:163], v[192:195], v[28:31]
	v_mfma_f32_16x16x32_bf16 v[24:27], v[168:171], v[192:195], v[24:27]
	v_mfma_f32_16x16x32_bf16 v[12:15], v[160:163], v[200:203], v[12:15]
	v_mfma_f32_16x16x32_bf16 v[8:11], v[168:171], v[200:203], v[8:11]
	s_setprio 0
.Lskp1_6:
	s_barrier
	s_add_u32 s64, s64, 0x40080
	s_addc_u32 s65, s65, 0
	s_add_i32 s66, s66, s4
	v_lshl_add_u64 v[146:147], s[64:65], 0, v[130:131]
	s_mov_b32 m0, s66
	s_nop 0
	global_load_lds_dwordx4 v[146:147], off
	v_lshl_add_u64 v[146:147], s[64:65], 0, v[134:135]
	s_add_i32 m0, s66, 0x2000
	s_nop 0
	global_load_lds_dwordx4 v[146:147], off
	s_waitcnt vmcnt(6)
	s_barrier
	s_cmp_lg_u32 s101, 0
	s_cbranch_scc1 .Lskp1_7
	s_setprio 1
	v_mfma_f32_16x16x32_bf16 v[52:55], v[204:207], v[172:175], v[52:55]
	v_mfma_f32_16x16x32_bf16 v[48:51], v[212:215], v[172:175], v[48:51]
	v_mfma_f32_16x16x32_bf16 v[36:39], v[204:207], v[180:183], v[36:39]
	v_mfma_f32_16x16x32_bf16 v[32:35], v[212:215], v[180:183], v[32:35]
	v_mfma_f32_16x16x32_bf16 v[20:23], v[204:207], v[188:191], v[20:23]
	v_mfma_f32_16x16x32_bf16 v[16:19], v[212:215], v[188:191], v[16:19]
	v_mfma_f32_16x16x32_bf16 v[4:7], v[204:207], v[196:199], v[4:7]
	v_mfma_f32_16x16x32_bf16 v[0:3], v[212:215], v[196:199], v[0:3]
	v_mfma_f32_16x16x32_bf16 v[52:55], v[208:211], v[176:179], v[52:55]
	v_mfma_f32_16x16x32_bf16 v[48:51], v[216:219], v[176:179], v[48:51]
	v_mfma_f32_16x16x32_bf16 v[36:39], v[208:211], v[184:187], v[36:39]
	v_mfma_f32_16x16x32_bf16 v[32:35], v[216:219], v[184:187], v[32:35]
	v_mfma_f32_16x16x32_bf16 v[20:23], v[208:211], v[192:195], v[20:23]
	v_mfma_f32_16x16x32_bf16 v[16:19], v[216:219], v[192:195], v[16:19]
	v_mfma_f32_16x16x32_bf16 v[4:7], v[208:211], v[200:203], v[4:7]
	v_mfma_f32_16x16x32_bf16 v[0:3], v[216:219], v[200:203], v[0:3]
	s_setprio 0
.Lskp1_7:
	s_add_i32 s94, s94, 2
	s_add_u32 s62, s62, 0x100
	s_addc_u32 s63, s63, 0
	s_add_u32 s61, s61, 0x100
	s_addc_u32 s93, s93, 0
	s_cmp_gt_u32 s94, 13
	s_barrier
	s_cbranch_scc0 .LBB0_255
	v_lshl_add_u32 v146, s60, 8, v139
	s_cmp_gt_i32 s58, 1
	s_mov_b64 s[62:63], -1
	s_cbranch_scc0 .LBB0_308
	s_cmp_gt_u32 s58, 3
	s_cbranch_scc0 .LBB0_289
	s_cmp_gt_u32 s58, 7
	s_cbranch_scc0 .LBB0_286
	s_cmp_gt_u32 s58, 15
	s_cbranch_scc0 .LBB0_279
	s_andn2_b64 vcc, exec, s[16:17]
	s_cbranch_vccnz .LBB0_278
	v_cmp_gt_i32_e32 vcc, s81, v146
	v_lshlrev_b32_e32 v148, 2, v138
	s_and_saveexec_b64 s[62:63], vcc
	s_cbranch_execz .LBB0_263
	v_add_u32_e32 v136, 0xffff0000, v146
	v_ashrrev_i32_e32 v147, 31, v146
	v_cmp_gt_i32_e32 vcc, s76, v146
	v_mov_b32_e32 v149, v137
	s_nop 0
	v_cndmask_b32_e32 v151, 0, v147, vcc
	v_cndmask_b32_e32 v150, v136, v146, vcc
	v_cndmask_b32_e32 v136, v156, v157, vcc
	v_lshl_add_u64 v[160:161], s[8:9], 0, v[136:137]
	v_lshlrev_b64 v[150:151], 8, v[150:151]
	v_lshl_add_u64 v[150:151], v[160:161], 0, v[150:151]
	v_lshl_add_u64 v[150:151], v[150:151], 0, v[148:149]
	global_store_dwordx4 v[150:151], v[124:127], off
	global_store_dwordx4 v[150:151], v[120:123], off offset:16

; template <bool NOMAX>
; __device__ __forceinline__ void attn_block(const Params& P, LAS unsigned char* lds, int qR0, int h, int kR0, int kR1, int ntiles, int jmax, int nlast, int qvalid) {
;     ...
;     for (int j = 0; j < ntiles; ++j) {
;         const int buf = j & 1;
;         if (j + 1 < ntiles) { const int Rn = (kR1 >= 0 && j + 1 >= 16) ? kR1 : kR0 + 64 * (j + 1);
;             attn_stage_issue(P, lds, st, Rn, buf ^ 1, tid); }
;         if (j <= jmax) {
;             const LAS unsigned char* kb = lds + L_K0 + buf * KBUF + r * 384; const LAS unsigned char* vb = lds + L_V0 + buf * VBUF + r * 128;
;             const LAS unsigned char* rkb = lds + L_RKT + j * 256 + 16 * hh;
;             f32x16 sacc[2];
; #pragma unroll
;             for (int kt = 0; kt < 2; ++kt) {
; #pragma unroll
;                 for (int e = 0; e < 16; ++e) sacc[kt][e] = 0.f;
; #pragma unroll
;                 for (int s = 0; s < 12; ++s) { const bf16x8 kf = *(const LAS bf16x8*)(kb + kt * (32 * 384) + (s >> 2) * 128 + oc[s & 3]); sacc[kt] = mfma32(kf, qf[s], sacc[kt]); }
;             }
; #pragma unroll
;             for (int kt = 0; kt < 2; ++kt)
; #pragma unroll
;                 for (int gq = 0; gq < 4; ++gq) { const f32x4 rk4 = *(const LAS f32x4*)(rkb + (32 * kt + 8 * gq) * 4);
; #pragma unroll
;                     for (int i = 0; i < 4; ++i) sacc[kt][4 * gq + i] *= rk4[i]; }
;             if (j == ntiles - 1 && nlast < 64) {
; #pragma unroll
;                 for (int kt = 0; kt < 2; ++kt)
; #pragma unroll
;                     for (int e = 0; e < 16; ++e) { const int key = 32 * kt + (e & 3) + 8 * (e >> 2) + 4 * hh; if (key >= nlast) sacc[kt][e] = -1e30f; } }
;             float mnew = 0.f;
;             if constexpr (!NOMAX) {
;                 float mx = sacc[0][0];
; #pragma unroll
;                 for (int kt = 0; kt < 2; ++kt)
; #pragma unroll
;                     for (int e = 0; e < 16; ++e) mx = fmaxf(mx, sacc[kt][e]);
;                 mx = fmaxf(mx, __shfl_xor(mx, 32));
;                 const float mcand = fmaxf(mrun, mx);
;                 if (__any(mcand > mrun + 8.0f)) { const float alpha = __builtin_amdgcn_exp2f(mrun - mcand); lrun *= alpha;
; #pragma unroll
;                     for (int dt = 0; dt < 4; ++dt)
; #pragma unroll
;                         for (int e = 0; e < 16; ++e) oacc[dt][e] *= alpha;
;                     mrun = mcand; }
.Lattn_tail_a:
	s_waitcnt vmcnt(0)
	s_addk_i32 s56, 0x100
	s_add_i32 s14, s14, 1
	v_add_u32_e32 v179, 0x80, v179
	v_add_u32_e32 v180, 0x80, v180
	s_cmp_eq_u32 s15, s56
	v_add_u32_e32 v181, 64, v181
	s_waitcnt vmcnt(0) lgkmcnt(0)
	s_barrier
	s_cbranch_scc1 .LBB0_1024
.LBB0_1019:
	s_and_b32 s57, s14, 1
	s_xor_b32 s12, s57, 1
	v_readfirstlane_b32 s13, v169
	s_ashr_i32 s13, s13, 6
	s_mul_i32 s58, s12, 0x6000
	s_mul_i32 s59, s13, 0xc00
	s_add_i32 s59, s58, s59
	s_lshl_b32 s12, s12, 14
	s_lshl_b32 s13, s13, 11
	s_add_i32 s60, s12, s13
	s_add_i32 s60, s60, 0xc000
	v_cmp_le_i32_e32 vcc, s14, v163
	s_cbranch_vccz .Lattn_inact_a
	s_mul_i32 s58, s57, 0x6000
	v_add_u32_e32 v253, s58, v177
	v_add_u32_e32 v214, v253, v168
	v_add_u32_e32 v215, v253, v167
	v_add_u32_e32 v216, v253, v166
	v_add_u32_e32 v217, v253, v165
	ds_read_b128 v[182:185], v214
	ds_read_b128 v[186:189], v215
	ds_read_b128 v[190:193], v216
	ds_read_b128 v[194:197], v217
	ds_read_b128 v[198:201], v214 offset:128
	ds_read_b128 v[202:205], v215 offset:128
	v_lshl_add_u32 v254, v181, v173, v170
	s_mov_b32 m0, s59
	s_nop 0
	global_load_lds_dwordx4 v254, s[18:19]
	v_lshl_add_u32 v254, v181, v174, v171
	s_add_i32 m0, s59, 0x400
	s_nop 0
	global_load_lds_dwordx4 v254, s[18:19]
	v_lshl_add_u32 v254, v181, v175, v172
	s_add_i32 m0, s59, 0x800
	s_nop 0
	global_load_lds_dwordx4 v254, s[18:19]
	s_waitcnt lgkmcnt(5)
	v_mfma_f32_32x32x16_bf16 v[64:79], v[182:185], v[100:103], 0
	ds_read_b128 v[206:209], v216 offset:128
	s_mov_b32 m0, s60
	s_nop 0
	global_load_lds_dwordx4 v180, s[18:19]
	v_add_u32_e32 v219, s56, v178
	s_waitcnt lgkmcnt(5)
	v_mfma_f32_32x32x16_bf16 v[64:79], v[186:189], v[104:107], v[64:79]
	ds_read_b128 v[210:213], v217 offset:128
	s_add_i32 m0, s60, 0x400
	s_nop 0
	global_load_lds_dwordx4 v179, s[18:19]
	v_add_u32_e32 v219, 0x14300, v219
	s_waitcnt lgkmcnt(5)
	v_mfma_f32_32x32x16_bf16 v[64:79], v[190:193], v[108:111], v[64:79]
	ds_read_b128 v[182:185], v214 offset:256
	v_lshl_add_u32 v218, s57, 14, v176
	s_waitcnt lgkmcnt(5)
	v_mfma_f32_32x32x16_bf16 v[64:79], v[194:197], v[112:115], v[64:79]
	ds_read_b128 v[186:189], v215 offset:256
	v_sub_u32_e32 v218, v218, v253
	s_waitcnt lgkmcnt(5)
	v_mfma_f32_32x32x16_bf16 v[64:79], v[198:201], v[116:119], v[64:79]
	ds_read_b128 v[190:193], v216 offset:256
	s_waitcnt lgkmcnt(5)
	v_mfma_f32_32x32x16_bf16 v[64:79], v[202:205], v[120:123], v[64:79]
	ds_read_b128 v[194:197], v217 offset:256
	s_waitcnt lgkmcnt(5)
	v_mfma_f32_32x32x16_bf16 v[64:79], v[206:209], v[124:127], v[64:79]
	ds_read_b128 v[198:201], v214 offset:12288
	s_waitcnt lgkmcnt(5)
	v_mfma_f32_32x32x16_bf16 v[64:79], v[210:213], v[128:131], v[64:79]
	ds_read_b128 v[202:205], v215 offset:12288
	s_waitcnt lgkmcnt(5)
	v_mfma_f32_32x32x16_bf16 v[64:79], v[182:185], v[132:135], v[64:79]
	ds_read_b128 v[206:209], v216 offset:12288
	s_waitcnt lgkmcnt(5)
	v_mfma_f32_32x32x16_bf16 v[64:79], v[186:189], v[136:139], v[64:79]
	ds_read_b128 v[210:213], v217 offset:12288
	ds_read_b128 v[232:235], v219
	s_waitcnt lgkmcnt(6)
	v_mfma_f32_32x32x16_bf16 v[64:79], v[190:193], v[140:143], v[64:79]
	ds_read_b128 v[182:185], v214 offset:12416
	ds_read_b128 v[236:239], v219 offset:32
	s_waitcnt lgkmcnt(7)
	v_mfma_f32_32x32x16_bf16 v[64:79], v[194:197], v[144:147], v[64:79]
	ds_read_b128 v[186:189], v215 offset:12416
	ds_read_b128 v[240:243], v219 offset:64
	s_waitcnt lgkmcnt(8)
	v_mfma_f32_32x32x16_bf16 v[80:95], v[198:201], v[100:103], 0
	ds_read_b128 v[190:193], v216 offset:12416
	ds_read_b128 v[244:247], v219 offset:96
	s_waitcnt lgkmcnt(9)
	v_mfma_f32_32x32x16_bf16 v[80:95], v[202:205], v[104:107], v[80:95]
	ds_read_b128 v[194:197], v217 offset:12416
	s_waitcnt lgkmcnt(9)
	v_mfma_f32_32x32x16_bf16 v[80:95], v[206:209], v[108:111], v[80:95]
	ds_read_b128 v[198:201], v214 offset:12544
	s_waitcnt lgkmcnt(9)
	v_mfma_f32_32x32x16_bf16 v[80:95], v[210:213], v[112:115], v[80:95]
	ds_read_b128 v[202:205], v215 offset:12544
	s_waitcnt lgkmcnt(9)
	v_mul_f32_e32 v64, v64, v232
	v_mul_f32_e32 v65, v65, v233
	v_mul_f32_e32 v66, v66, v234
	v_mul_f32_e32 v67, v67, v235
	v_exp_f32_e32 v64, v64
	s_waitcnt lgkmcnt(8)
	v_mfma_f32_32x32x16_bf16 v[80:95], v[182:185], v[116:119], v[80:95]
	ds_read_b128 v[206:209], v216 offset:12544
	s_waitcnt lgkmcnt(8)
	v_mul_f32_e32 v68, v68, v236
	v_exp_f32_e32 v65, v65
	v_mul_f32_e32 v69, v69, v237
	v_exp_f32_e32 v66, v66
	v_mul_f32_e32 v70, v70, v238
	s_waitcnt lgkmcnt(7)
	v_mfma_f32_32x32x16_bf16 v[80:95], v[186:189], v[120:123], v[80:95]
	ds_read_b128 v[210:213], v217 offset:12544
	v_exp_f32_e32 v67, v67
	v_mul_f32_e32 v71, v71, v239
	v_add_u32_e32 v214, v214, v218
	v_add_u32_e32 v215, v215, v218
	v_add_u32_e32 v216, v216, v218
	v_add_u32_e32 v217, v217, v218
	s_waitcnt lgkmcnt(6)
	v_mfma_f32_32x32x16_bf16 v[80:95], v[190:193], v[124:127], v[80:95]
	ds_read_b128 v[182:185], v214 offset:49152
	v_exp_f32_e32 v68, v68
	v_cvt_pk_bf16_f32 v222, v64, v65
	v_exp_f32_e32 v69, v69
	v_cvt_pk_bf16_f32 v223, v66, v67
	v_exp_f32_e32 v70, v70
	s_waitcnt lgkmcnt(5)
	v_mfma_f32_32x32x16_bf16 v[80:95], v[194:197], v[128:131], v[80:95]
	ds_read_b128 v[186:189], v214 offset:53248
	v_exp_f32_e32 v71, v71
	v_cvt_pk_bf16_f32 v224, v68, v69
	v_cvt_pk_bf16_f32 v225, v70, v71
	v_mul_f32_e32 v72, v72, v240
	v_mul_f32_e32 v73, v73, v241
	s_waitcnt lgkmcnt(5)
	v_mfma_f32_32x32x16_bf16 v[80:95], v[198:201], v[132:135], v[80:95]
	ds_read_b128 v[190:193], v214 offset:57344
	v_mul_f32_e32 v74, v74, v242
	v_mul_f32_e32 v75, v75, v243
	v_exp_f32_e32 v72, v72
	v_mul_f32_e32 v76, v76, v244
	v_exp_f32_e32 v73, v73
	s_waitcnt lgkmcnt(5)
; #define LAS __attribute__((address_space(3)))
; __device__ __forceinline__ f32x16 mfma32(bf16x8 a, bf16x8 b, f32x16 c) { return __builtin_amdgcn_mfma_f32_32x32x16_bf16(a, b, c, 0, 0, 0); }
; __device__ __forceinline__ void attn_stage_issue(const Params& P, LAS unsigned char* lds, const AttnStage& st, int R0, int buf, int tid) {
;     ...
;     for (int i = 0; i < 3; ++i) __builtin_amdgcn_global_load_lds((const unsigned*)(ws + (st.kofs[i] + (unsigned)R0 * st.kstr[i])), (LAS unsigned*)(lds + L_K0 + buf * KBUF + (w * 3 + i) * 1024), 16, 0, 0);
; #pragma unroll
;     for (int i = 0; i < 2; ++i) __builtin_amdgcn_global_load_lds((const unsigned*)(ws + (st.vofs[i] + (unsigned)R0 * 2u)), (LAS unsigned*)(lds + L_V0 + buf * VBUF + (w * 2 + i) * 1024), 16, 0, 0);
; template <bool NOMAX>
; __device__ __forceinline__ void attn_block(const Params& P, LAS unsigned char* lds, int qR0, int h, int kR0, int kR1, int ntiles, int jmax, int nlast, int qvalid) {
;     ...
;             for (int kt = 0; kt < 2; ++kt)
; #pragma unroll
;                 for (int e = 0; e < 16; ++e) { const float p = __builtin_amdgcn_exp2f(NOMAX ? sacc[kt][e] : sacc[kt][e] - mnew); sacc[kt][e] = p; ps += p; }
;             lrun += ps;
;             bf16x8 pf[2][2];
; #pragma unroll
;             for (int kt = 0; kt < 2; ++kt)
; #pragma unroll
;                 for (int s2 = 0; s2 < 2; ++s2) { u32x4 v; v.x = pk2(sacc[kt][8 * s2 + 0], sacc[kt][8 * s2 + 1]); v.y = pk2(sacc[kt][8 * s2 + 2], sacc[kt][8 * s2 + 3]); v.z = pk2(sacc[kt][8 * s2 + 4], sacc[kt][8 * s2 + 5]); v.w = pk2(sacc[kt][8 * s2 + 6], sacc[kt][8 * s2 + 7]); pf[kt][s2] = *(const bf16x8*)&v; }
; #pragma unroll
;             for (int dt = 0; dt < 4; ++dt)
; #pragma unroll
;                 for (int kt = 0; kt < 2; ++kt)
; #pragma unroll
;                     for (int s2 = 0; s2 < 2; ++s2) { const bf16x8 vf = *(const LAS bf16x8*)(vb + dt * (32 * 128) + oc[2 * kt + s2]);
;                         oacc[dt] = mfma32(vf, pf[kt][s2], oacc[dt]); }
;         }
;         asm volatile("s_waitcnt vmcnt(0)" ::: "memory");
;         __syncthreads();
	v_mfma_f32_32x32x16_bf16 v[80:95], v[202:205], v[136:139], v[80:95]
	ds_read_b128 v[194:197], v214 offset:61440
	v_mul_f32_e32 v77, v77, v245
	v_exp_f32_e32 v74, v74
	v_mul_f32_e32 v78, v78, v246
	v_exp_f32_e32 v75, v75
	v_mul_f32_e32 v79, v79, v247
	s_waitcnt lgkmcnt(5)
	v_mfma_f32_32x32x16_bf16 v[80:95], v[206:209], v[140:143], v[80:95]
	ds_read_b128 v[198:201], v215 offset:49152
	v_exp_f32_e32 v76, v76
	v_cvt_pk_bf16_f32 v226, v72, v73
	v_exp_f32_e32 v77, v77
	v_cvt_pk_bf16_f32 v227, v74, v75
	ds_read_b128 v[232:235], v219 offset:128
	ds_read_b128 v[236:239], v219 offset:160
	s_waitcnt lgkmcnt(7)
	v_mfma_f32_32x32x16_bf16 v[80:95], v[210:213], v[144:147], v[80:95]
	ds_read_b128 v[202:205], v215 offset:53248
	v_exp_f32_e32 v78, v78
	v_exp_f32_e32 v79, v79
	v_cvt_pk_bf16_f32 v228, v76, v77
	v_cvt_pk_bf16_f32 v229, v78, v79
	ds_read_b128 v[240:243], v219 offset:192
	ds_read_b128 v[244:247], v219 offset:224
	s_waitcnt lgkmcnt(9)
	v_mfma_f32_32x32x16_bf16 v[48:63], v[182:185], v[222:225], v[48:63]
	ds_read_b128 v[206:209], v215 offset:57344
	v_add_f32_e32 v231, v64, v65
	v_add_f32_e32 v231, v66, v231
	v_add_f32_e32 v231, v67, v231
	v_add_f32_e32 v231, v68, v231
	s_waitcnt lgkmcnt(9)
	v_mfma_f32_32x32x16_bf16 v[32:47], v[186:189], v[222:225], v[32:47]
	ds_read_b128 v[210:213], v215 offset:61440
	v_add_f32_e32 v231, v69, v231
	v_add_f32_e32 v231, v70, v231
	v_add_f32_e32 v231, v71, v231
	v_add_f32_e32 v231, v72, v231
	s_waitcnt lgkmcnt(9)
	v_mfma_f32_32x32x16_bf16 v[16:31], v[190:193], v[222:225], v[16:31]
	ds_read_b128 v[182:185], v216 offset:49152
	v_add_f32_e32 v231, v73, v231
	v_add_f32_e32 v231, v74, v231
	v_add_f32_e32 v231, v75, v231
	v_add_f32_e32 v231, v76, v231
	s_waitcnt lgkmcnt(9)
	v_mfma_f32_32x32x16_bf16 v[0:15], v[194:197], v[222:225], v[0:15]
	ds_read_b128 v[186:189], v216 offset:53248
	s_waitcnt lgkmcnt(8)
	v_mul_f32_e32 v80, v80, v232
	v_mul_f32_e32 v81, v81, v233
	v_mul_f32_e32 v82, v82, v234
	v_mul_f32_e32 v83, v83, v235
	v_mfma_f32_32x32x16_bf16 v[48:63], v[198:201], v[226:229], v[48:63]
	ds_read_b128 v[190:193], v216 offset:57344
	v_exp_f32_e32 v80, v80
	s_waitcnt lgkmcnt(8)
	v_mul_f32_e32 v84, v84, v236
	v_exp_f32_e32 v81, v81
	v_mul_f32_e32 v85, v85, v237
	s_waitcnt lgkmcnt(7)
	v_mfma_f32_32x32x16_bf16 v[32:47], v[202:205], v[226:229], v[32:47]
	ds_read_b128 v[194:197], v216 offset:61440
	v_exp_f32_e32 v82, v82
	v_mul_f32_e32 v86, v86, v238
	v_exp_f32_e32 v83, v83
	v_mul_f32_e32 v87, v87, v239
	s_waitcnt lgkmcnt(5)
	v_mfma_f32_32x32x16_bf16 v[16:31], v[206:209], v[226:229], v[16:31]
	ds_read_b128 v[198:201], v217 offset:49152
	v_exp_f32_e32 v84, v84
	v_cvt_pk_bf16_f32 v248, v80, v81
	v_exp_f32_e32 v85, v85
	v_cvt_pk_bf16_f32 v249, v82, v83
	s_waitcnt lgkmcnt(5)
	v_mfma_f32_32x32x16_bf16 v[0:15], v[210:213], v[226:229], v[0:15]
	ds_read_b128 v[202:205], v217 offset:53248
	v_exp_f32_e32 v86, v86
	v_exp_f32_e32 v87, v87
	v_cvt_pk_bf16_f32 v250, v84, v85
	v_cvt_pk_bf16_f32 v251, v86, v87
	v_add_f32_e32 v231, v77, v231
	v_add_f32_e32 v231, v78, v231
	v_add_f32_e32 v231, v79, v231
	s_waitcnt lgkmcnt(5)
	v_mfma_f32_32x32x16_bf16 v[48:63], v[182:185], v[248:251], v[48:63]
	ds_read_b128 v[206:209], v217 offset:57344
	v_mul_f32_e32 v88, v88, v240
	v_mul_f32_e32 v89, v89, v241
	v_mul_f32_e32 v90, v90, v242
	v_mul_f32_e32 v91, v91, v243
	v_exp_f32_e32 v88, v88
	s_waitcnt lgkmcnt(5)
	v_mfma_f32_32x32x16_bf16 v[32:47], v[186:189], v[248:251], v[32:47]
	ds_read_b128 v[210:213], v217 offset:61440
	v_mul_f32_e32 v92, v92, v244
	v_exp_f32_e32 v89, v89
	v_mul_f32_e32 v93, v93, v245
	v_exp_f32_e32 v90, v90
	v_mul_f32_e32 v94, v94, v246
	s_waitcnt lgkmcnt(5)
	v_mfma_f32_32x32x16_bf16 v[16:31], v[190:193], v[248:251], v[16:31]
	v_exp_f32_e32 v91, v91
	v_mul_f32_e32 v95, v95, v247
	v_exp_f32_e32 v92, v92
	v_cvt_pk_bf16_f32 v64, v88, v89
	v_exp_f32_e32 v93, v93
	s_waitcnt lgkmcnt(4)
	v_mfma_f32_32x32x16_bf16 v[0:15], v[194:197], v[248:251], v[0:15]
	v_cvt_pk_bf16_f32 v65, v90, v91
	v_exp_f32_e32 v94, v94
	v_exp_f32_e32 v95, v95
	v_cvt_pk_bf16_f32 v66, v92, v93
	v_cvt_pk_bf16_f32 v67, v94, v95
	v_add_f32_e32 v252, v80, v81
	v_add_f32_e32 v252, v82, v252
	s_waitcnt lgkmcnt(3)
	v_mfma_f32_32x32x16_bf16 v[48:63], v[198:201], v[64:67], v[48:63]
	v_add_f32_e32 v252, v83, v252
	v_add_f32_e32 v252, v84, v252
	v_add_f32_e32 v252, v85, v252
	v_add_f32_e32 v252, v86, v252
	s_waitcnt lgkmcnt(2)
	v_mfma_f32_32x32x16_bf16 v[32:47], v[202:205], v[64:67], v[32:47]
	v_add_f32_e32 v252, v87, v252
	v_add_f32_e32 v252, v88, v252
	v_add_f32_e32 v252, v89, v252
	v_add_f32_e32 v252, v90, v252
	s_waitcnt lgkmcnt(1)
	v_mfma_f32_32x32x16_bf16 v[16:31], v[206:209], v[64:67], v[16:31]
	v_add_f32_e32 v252, v91, v252
	v_add_f32_e32 v252, v92, v252
	v_add_f32_e32 v252, v93, v252
	v_add_f32_e32 v252, v94, v252
	s_waitcnt lgkmcnt(0)
	v_mfma_f32_32x32x16_bf16 v[0:15], v[210:213], v[64:67], v[0:15]
	v_add_f32_e32 v252, v95, v252
	v_add_f32_e32 v231, v231, v252
	v_add_f32_e32 v164, v164, v231
	s_branch .Lattn_tail_a
.Lattn_inact_a:
	v_lshl_add_u32 v64, v181, v173, v170
	s_mov_b32 m0, s59
	s_nop 0
	global_load_lds_dwordx4 v64, s[18:19]
	v_lshl_add_u32 v64, v181, v174, v171
	s_add_i32 m0, s59, 0x400
	s_nop 0
	global_load_lds_dwordx4 v64, s[18:19]
	v_lshl_add_u32 v64, v181, v175, v172
	s_add_i32 m0, s59, 0x800
	s_nop 0
	global_load_lds_dwordx4 v64, s[18:19]
	s_mov_b32 m0, s60
	s_nop 0
	global_load_lds_dwordx4 v180, s[18:19]
	s_add_i32 m0, s60, 0x400
	s_nop 0
	global_load_lds_dwordx4 v179, s[18:19]
	s_branch .Lattn_tail_a

;     __device__ __forceinline__ bool next(int i, Unit& u) const {
;         int L = (i / UPT) * G + c;
;         constexpr int n0 = nM0 * nN0, n1 = nM1 * nN1, n2 = nM2 * nN2;
;         if (L < n0) { tile_of(L, nM0, nN0, u.pm, u.pn); u.g = (UPT > 1) ? (i % UPT) : 0; return true; }
.LBB0_1364:
	s_add_i32 s38, s38, 1
	s_mul_i32 s17, s38, s68
	s_add_i32 s17, s17, s2
	s_cmpk_lt_i32 s17, 0x1616
	s_cselect_b64 s[30:31], -1, 0
	s_cmpk_gt_i32 s17, 0x1615
	s_cselect_b64 s[14:15], -1, 0
	s_and_b64 vcc, exec, s[14:15]
	s_cbranch_vccnz .LBB0_1370
	s_sub_i32 s99, s17, 0x1567
	s_and_b32 s100, s99, 7
	s_cmp_eq_u32 s100, 0
	s_cbranch_scc0 .Lrmp7_a
	s_lshr_b32 s100, s99, 3
	s_cmp_lt_u32 s100, 20
	s_cbranch_scc0 .Lrmp7_a
	s_add_i32 s17, s100, 0x1600
	s_cmp_ge_u32 s100, 7
	s_addc_u32 s17, s17, 0
	s_cmp_ge_u32 s100, 14
	s_addc_u32 s17, s17, 0
	s_branch .Lrmp7_c
.Lrmp7_a:
	s_cmp_lt_i32 s17, 0x1600
	s_cbranch_scc1 .Lrmp7_c
	s_sub_i32 s99, s17, 0x1600
	s_cmp_eq_u32 s99, 7
	s_cbranch_scc1 .Lrmp7_c
	s_cmp_eq_u32 s99, 15
	s_cbranch_scc1 .Lrmp7_c
	s_cmp_gt_u32 s99, 7
	s_cselect_b32 s100, 1, 0
	s_cmp_gt_u32 s99, 15
	s_cselect_b32 s17, 1, 0
	s_sub_i32 s99, s99, s100
	s_sub_i32 s99, s99, s17
	s_lshl_b32 s99, s99, 3
	s_add_i32 s17, s99, 0x1567
.Lrmp7_c:
	s_ashr_i32 s16, s17, 31
	s_lshr_b32 s16, s16, 29
	s_add_i32 s18, s17, s16
	s_and_b32 s16, s18, -8
	s_sub_i32 s19, s17, s16
	s_cmp_gt_i32 s19, 5
	s_mov_b64 s[16:17], -1
	s_cbranch_scc0 .LBB0_1367
	s_mul_i32 s16, s19, 0x2c2
	s_add_i32 s20, s16, 6
	s_mov_b64 s[16:17], 0

; template <class Epi, class Sched>
; __device__ __forceinline__ void gemm_phase(LAS unsigned char* lds, const int K, const Sched& S, const Epi& E) {
;     ...
;         for (int a = 0; a < 2; ++a)
; #pragma unroll
;             for (int b = 0; b < 2; ++b)
; #pragma unroll
;                 for (int m = 0; m < 4; ++m)
; #pragma unroll
;                     for (int n = 0; n < 2; ++n) acc[a][b][m][n] = (f32x4){0.f, 0.f, 0.f, 0.f};
;         cur = nxt; cA = nA; cB = nB; ++ui;
;     __device__ __forceinline__ void operator()(Acc& acc, const Unit& u, int wr, int wc, int fr, int fq) const {
;     ...
;             bf16_t* O = (bf16_t*)(ws + R_A); const float* ssq = (const float*)(ws + W_SSQ2);
;             float rsv[2][4];
; #pragma unroll
;             for (int ai = 0; ai < 2; ++ai)
; #pragma unroll
;                 for (int m = 0; m < 4; ++m) rsv[ai][m] = ssq[row0 + ai * 128 + m * 16];
.LBB0_1370:
	s_ashr_i32 s19, s18, 31
	s_lshl_b64 s[20:21], s[18:19], 19
	s_add_u32 s20, s33, s20
	s_addc_u32 s21, s34, s21
	s_and_b64 s[22:23], s[30:31], exec
	s_cselect_b32 s19, s21, s27
	s_cselect_b32 s44, s20, s26
	s_ashr_i32 s17, s16, 31
	s_lshl_b64 s[22:23], s[16:17], 19
	s_add_u32 s22, s3, s22
	s_addc_u32 s23, s4, s23
	s_and_b64 s[30:31], s[30:31], exec
	s_cselect_b32 s17, s23, s29
	s_cselect_b32 s45, s22, s28
	s_add_u32 s26, s26, 0x40080
	s_addc_u32 s27, s27, 0
	s_add_u32 s46, s28, 0x100
	v_mov_b32_e32 v0, 0
	s_addc_u32 s47, s29, 0
	s_mov_b32 s48, -2
	v_mov_b32_e32 v1, v0
	v_mov_b32_e32 v2, v0
	v_mov_b32_e32 v3, v0
	v_mov_b32_e32 v4, v0
	v_mov_b32_e32 v5, v0
	v_mov_b32_e32 v6, v0
	v_mov_b32_e32 v7, v0
	v_mov_b32_e32 v16, v0
	v_mov_b32_e32 v17, v0
	v_mov_b32_e32 v18, v0
	v_mov_b32_e32 v19, v0
	v_mov_b32_e32 v20, v0
	v_mov_b32_e32 v21, v0
	v_mov_b32_e32 v22, v0
	v_mov_b32_e32 v23, v0
	v_mov_b32_e32 v32, v0
	v_mov_b32_e32 v33, v0
	v_mov_b32_e32 v34, v0
	v_mov_b32_e32 v35, v0
	v_mov_b32_e32 v36, v0
	v_mov_b32_e32 v37, v0
	v_mov_b32_e32 v38, v0
	v_mov_b32_e32 v39, v0
	v_mov_b32_e32 v48, v0
	v_mov_b32_e32 v49, v0
	v_mov_b32_e32 v50, v0
	v_mov_b32_e32 v51, v0
	v_mov_b32_e32 v52, v0
	v_mov_b32_e32 v53, v0
	v_mov_b32_e32 v54, v0
	v_mov_b32_e32 v55, v0
	v_mov_b32_e32 v8, v0
	v_mov_b32_e32 v9, v0
	v_mov_b32_e32 v10, v0
	v_mov_b32_e32 v11, v0
	v_mov_b32_e32 v12, v0
	v_mov_b32_e32 v13, v0
	v_mov_b32_e32 v14, v0
	v_mov_b32_e32 v15, v0
	v_mov_b32_e32 v24, v0
	v_mov_b32_e32 v25, v0
	v_mov_b32_e32 v26, v0
	v_mov_b32_e32 v27, v0
	v_mov_b32_e32 v28, v0
	v_mov_b32_e32 v29, v0
	v_mov_b32_e32 v30, v0
	v_mov_b32_e32 v31, v0
	v_mov_b32_e32 v40, v0
	v_mov_b32_e32 v41, v0
	v_mov_b32_e32 v42, v0
	v_mov_b32_e32 v43, v0
	v_mov_b32_e32 v44, v0
	v_mov_b32_e32 v45, v0
	v_mov_b32_e32 v46, v0
	v_mov_b32_e32 v47, v0
	v_mov_b32_e32 v56, v0
	v_mov_b32_e32 v57, v0
	v_mov_b32_e32 v58, v0
	v_mov_b32_e32 v59, v0
	v_mov_b32_e32 v60, v0
	v_mov_b32_e32 v61, v0
	v_mov_b32_e32 v62, v0
	v_mov_b32_e32 v63, v0
	v_mov_b32_e32 v64, v0
	v_mov_b32_e32 v65, v0
	v_mov_b32_e32 v66, v0
	v_mov_b32_e32 v67, v0
	v_mov_b32_e32 v72, v0
	v_mov_b32_e32 v73, v0
	v_mov_b32_e32 v74, v0
	v_mov_b32_e32 v75, v0
	v_mov_b32_e32 v80, v0
	v_mov_b32_e32 v81, v0
	v_mov_b32_e32 v82, v0
	v_mov_b32_e32 v83, v0
	v_mov_b32_e32 v88, v0
	v_mov_b32_e32 v89, v0
	v_mov_b32_e32 v90, v0
	v_mov_b32_e32 v91, v0
	v_mov_b32_e32 v96, v0
	v_mov_b32_e32 v97, v0
	v_mov_b32_e32 v98, v0
	v_mov_b32_e32 v99, v0
	v_mov_b32_e32 v104, v0
	v_mov_b32_e32 v105, v0
	v_mov_b32_e32 v106, v0
	v_mov_b32_e32 v107, v0
	v_mov_b32_e32 v112, v0
	v_mov_b32_e32 v113, v0
	v_mov_b32_e32 v114, v0
	v_mov_b32_e32 v115, v0
	v_mov_b32_e32 v116, v0
	v_mov_b32_e32 v117, v0
	v_mov_b32_e32 v118, v0
	v_mov_b32_e32 v119, v0
	v_mov_b32_e32 v68, v0
	v_mov_b32_e32 v69, v0
	v_mov_b32_e32 v70, v0
	v_mov_b32_e32 v71, v0
	v_mov_b32_e32 v76, v0
	v_mov_b32_e32 v77, v0
	v_mov_b32_e32 v78, v0
	v_mov_b32_e32 v79, v0
	v_mov_b32_e32 v84, v0
	v_mov_b32_e32 v85, v0
	v_mov_b32_e32 v86, v0
	v_mov_b32_e32 v87, v0
	v_mov_b32_e32 v92, v0
	v_mov_b32_e32 v93, v0
	v_mov_b32_e32 v94, v0
	v_mov_b32_e32 v95, v0
	v_mov_b32_e32 v100, v0
	v_mov_b32_e32 v101, v0
	v_mov_b32_e32 v102, v0
	v_mov_b32_e32 v103, v0
	v_mov_b32_e32 v108, v0
	v_mov_b32_e32 v109, v0
	v_mov_b32_e32 v110, v0
	v_mov_b32_e32 v111, v0
	v_mov_b32_e32 v120, v0
	v_mov_b32_e32 v121, v0
	v_mov_b32_e32 v122, v0
	v_mov_b32_e32 v123, v0
	v_mov_b32_e32 v124, v0
	v_mov_b32_e32 v125, v0
	v_mov_b32_e32 v126, v0
	v_mov_b32_e32 v127, v0
	v_lshl_add_u32 v240, s24, 8, v150
	v_ashrrev_i32_e32 v241, 31, v240
	v_lshl_add_u64 v[240:241], v[240:241], 2, s[10:11]
	global_load_dword v232, v[240:241], off
	global_load_dword v233, v[240:241], off offset:64
	global_load_dword v234, v[240:241], off offset:128
	global_load_dword v235, v[240:241], off offset:192
	global_load_dword v236, v[240:241], off offset:512
	global_load_dword v237, v[240:241], off offset:576
	global_load_dword v238, v[240:241], off offset:640
	global_load_dword v239, v[240:241], off offset:704
	s_cmpk_eq_i32 s24, 0x100
	s_cselect_b64 vcc, -1, 0
.LBB0_1371:
	ds_read_b128 v[142:145], v152
	ds_read_b128 v[146:149], v152 offset:1024
	ds_read_b128 v[156:159], v152 offset:2048
	ds_read_b128 v[160:163], v152 offset:3072
	s_add_u32 s28, s26, 0xfffc0080
	s_addc_u32 s29, s27, -1
	s_cmp_eq_u32 s48, 12
	s_cselect_b32 s31, s19, s29
	s_cselect_b32 s30, s44, s28
	s_cselect_b32 s29, s17, s47
	s_cselect_b32 s28, s45, s46
	v_lshl_add_u64 v[196:197], s[26:27], 0, v[138:139]
	s_add_i32 m0, s5, 0xc000
	ds_read_b128 v[164:167], v153
	ds_read_b128 v[168:171], v153 offset:1024
	ds_read_b128 v[172:175], v153 offset:2048
	ds_read_b128 v[176:179], v153 offset:3072
	ds_read_b128 v[180:183], v153 offset:4096
	ds_read_b128 v[184:187], v153 offset:5120
	ds_read_b128 v[188:191], v153 offset:6144
	ds_read_b128 v[192:195], v153 offset:7168
	global_load_lds_dwordx4 v[196:197], off
	v_lshl_add_u64 v[196:197], s[26:27], 0, v[140:141]
	s_add_i32 m0, s5, 0xe000
	s_nop 0
	global_load_lds_dwordx4 v[196:197], off
	s_waitcnt lgkmcnt(8)
	s_barrier
; #define PG8_STAGE(bufoff, gbase, voff) do { _Pragma("unroll") for (int _i = 0; _i < 2; ++_i) \
;         __builtin_amdgcn_global_load_lds((const unsigned*)((const char*)(gbase) + (voff)[_i]), (LAS unsigned*)(lds + (bufoff) + ldsw + _i * 8192), 16, 0, 0); } while (0)
; #define PG8_LDA(dst, b, h) do { _Pragma("unroll") for (int m = 0; m < 4; ++m) _Pragma("unroll") for (int k = 0; k < 2; ++k) dst[m][k] = *(const LAS bf16x8*)(lds + PG8_SA(b, h) + aoff + m * 2048 + k * 1024); } while (0)
; #define PG8_LDB(dst, b, h) do { _Pragma("unroll") for (int n = 0; n < 2; ++n) _Pragma("unroll") for (int k = 0; k < 2; ++k) dst[n][k] = *(const LAS bf16x8*)(lds + PG8_SB(b, h) + boff + n * 2048 + k * 1024); } while (0)
; #define PG8_MMA(ai, bj, At, Bt) do { __builtin_amdgcn_s_setprio(1); _Pragma("unroll") for (int m = 0; m < 4; ++m) _Pragma("unroll") for (int n = 0; n < 2; ++n) _Pragma("unroll") for (int k = 0; k < 2; ++k) \
;         acc[ai][bj][m][n] = __builtin_amdgcn_mfma_f32_16x16x32_bf16(Bt[n][k], At[m][k], acc[ai][bj][m][n], 0, 0, 0); __builtin_amdgcn_s_setprio(0); } while (0)
; #define PG8_WAIT_V(n) asm volatile("s_waitcnt vmcnt(" #n ")" ::: "memory")
; #define PG8_WAIT_L(n) asm volatile("s_waitcnt lgkmcnt(" #n ")" ::: "memory")
; #define PG8_BAR __builtin_amdgcn_s_barrier()
; #define PG8_SCHED __builtin_amdgcn_sched_barrier(0)
; template <class Epi, class Sched>
; __device__ __forceinline__ void gemm_phase(LAS unsigned char* lds, const int K, const Sched& S, const Epi& E) {
;     ...
;             PG8_LDB(B0, 0, 0); PG8_SCHED; PG8_LDA(At, 0, 0); PG8_STAGE(PG8_SA(1, 1), a1 + hstep, voffA);
;             PG8_WAIT_L(8); PG8_BAR; PG8_WAIT_L(0); PG8_MMA(0, 0, At, B0); PG8_BAR; PG8_SCHED;
;             PG8_LDB(B1, 0, 1); PG8_STAGE(PG8_SB(0, 0), b2, voffB);
;             PG8_BAR; PG8_WAIT_L(0); PG8_MMA(0, 1, At, B1); PG8_BAR;
;             PG8_LDA(At, 0, 1); PG8_STAGE(PG8_SA(0, 0), a2, voffA);
;             PG8_BAR; PG8_WAIT_L(0); PG8_MMA(1, 0, At, B0); PG8_BAR; PG8_SCHED;
;             PG8_STAGE(PG8_SB(0, 1), b2 + hstep, voffB);
;             PG8_WAIT_V(6); PG8_BAR; PG8_MMA(1, 1, At, B1); PG8_BAR;
	s_waitcnt lgkmcnt(0)
	s_setprio 1
	s_waitcnt lgkmcnt(0)
	v_mfma_f32_16x16x32_bf16 v[124:127], v[142:145], v[164:167], v[124:127]
	v_mfma_f32_16x16x32_bf16 v[120:123], v[156:159], v[164:167], v[120:123]
	v_mfma_f32_16x16x32_bf16 v[108:111], v[142:145], v[172:175], v[108:111]
	v_mfma_f32_16x16x32_bf16 v[100:103], v[156:159], v[172:175], v[100:103]
	v_mfma_f32_16x16x32_bf16 v[92:95], v[142:145], v[180:183], v[92:95]
	v_mfma_f32_16x16x32_bf16 v[84:87], v[156:159], v[180:183], v[84:87]
	v_mfma_f32_16x16x32_bf16 v[76:79], v[142:145], v[188:191], v[76:79]
	v_mfma_f32_16x16x32_bf16 v[68:71], v[156:159], v[188:191], v[68:71]
	v_mfma_f32_16x16x32_bf16 v[124:127], v[146:149], v[168:171], v[124:127]
	v_mfma_f32_16x16x32_bf16 v[120:123], v[160:163], v[168:171], v[120:123]
	v_mfma_f32_16x16x32_bf16 v[108:111], v[146:149], v[176:179], v[108:111]
	v_mfma_f32_16x16x32_bf16 v[100:103], v[160:163], v[176:179], v[100:103]
	v_mfma_f32_16x16x32_bf16 v[92:95], v[146:149], v[184:187], v[92:95]
	v_mfma_f32_16x16x32_bf16 v[84:87], v[160:163], v[184:187], v[84:87]
	v_mfma_f32_16x16x32_bf16 v[76:79], v[146:149], v[192:195], v[76:79]
	v_mfma_f32_16x16x32_bf16 v[68:71], v[160:163], v[192:195], v[68:71]
	s_setprio 0
	s_barrier
	s_add_i32 s49, s41, s1
	v_lshl_add_u64 v[212:213], s[28:29], 0, v[130:131]
	s_mov_b32 m0, s49
	ds_read_b128 v[196:199], v154
	ds_read_b128 v[200:203], v154 offset:1024
	ds_read_b128 v[204:207], v154 offset:2048
	ds_read_b128 v[208:211], v154 offset:3072
	global_load_lds_dwordx4 v[212:213], off
	v_lshl_add_u64 v[214:215], s[28:29], 0, v[134:135]
	s_add_i32 m0, s49, 0x2000
	s_nop 0
	global_load_lds_dwordx4 v[214:215], off
	s_barrier
	s_waitcnt lgkmcnt(0)
	s_setprio 1
	s_waitcnt lgkmcnt(0)
	v_mfma_f32_16x16x32_bf16 v[116:119], v[196:199], v[164:167], v[116:119]
	v_mfma_f32_16x16x32_bf16 v[112:115], v[204:207], v[164:167], v[112:115]
	v_mfma_f32_16x16x32_bf16 v[104:107], v[196:199], v[172:175], v[104:107]
	v_mfma_f32_16x16x32_bf16 v[96:99], v[204:207], v[172:175], v[96:99]
	v_mfma_f32_16x16x32_bf16 v[88:91], v[196:199], v[180:183], v[88:91]
	v_mfma_f32_16x16x32_bf16 v[80:83], v[204:207], v[180:183], v[80:83]
	v_mfma_f32_16x16x32_bf16 v[72:75], v[196:199], v[188:191], v[72:75]
	v_mfma_f32_16x16x32_bf16 v[64:67], v[204:207], v[188:191], v[64:67]
	v_mfma_f32_16x16x32_bf16 v[116:119], v[200:203], v[168:171], v[116:119]
	v_mfma_f32_16x16x32_bf16 v[112:115], v[208:211], v[168:171], v[112:115]
	v_mfma_f32_16x16x32_bf16 v[104:107], v[200:203], v[176:179], v[104:107]
	v_mfma_f32_16x16x32_bf16 v[96:99], v[208:211], v[176:179], v[96:99]
	v_mfma_f32_16x16x32_bf16 v[88:91], v[200:203], v[184:187], v[88:91]
	v_mfma_f32_16x16x32_bf16 v[80:83], v[208:211], v[184:187], v[80:83]
	v_mfma_f32_16x16x32_bf16 v[72:75], v[200:203], v[192:195], v[72:75]
	v_mfma_f32_16x16x32_bf16 v[64:67], v[208:211], v[192:195], v[64:67]
	s_setprio 0
	s_mov_b32 m0, s5
	v_lshl_add_u64 v[216:217], s[30:31], 0, v[128:129]
	s_barrier
	ds_read_b128 v[164:167], v153 offset:16384
	ds_read_b128 v[168:171], v153 offset:17408
	ds_read_b128 v[172:175], v153 offset:18432
	ds_read_b128 v[176:179], v153 offset:19456
	ds_read_b128 v[180:183], v153 offset:20480
	ds_read_b128 v[184:187], v153 offset:21504
	ds_read_b128 v[188:191], v153 offset:22528
	ds_read_b128 v[192:195], v153 offset:23552
	global_load_lds_dwordx4 v[216:217], off
	v_lshl_add_u64 v[218:219], s[30:31], 0, v[132:133]
	s_mov_b32 m0, s35
	s_nop 0
	global_load_lds_dwordx4 v[218:219], off
	s_barrier
	s_waitcnt lgkmcnt(0)
	s_cbranch_vccnz .Lskp7_2
	s_setprio 1
	s_waitcnt lgkmcnt(0)
	v_mfma_f32_16x16x32_bf16 v[60:63], v[142:145], v[164:167], v[60:63]
	v_mfma_f32_16x16x32_bf16 v[56:59], v[156:159], v[164:167], v[56:59]
	v_mfma_f32_16x16x32_bf16 v[44:47], v[142:145], v[172:175], v[44:47]
	v_mfma_f32_16x16x32_bf16 v[40:43], v[156:159], v[172:175], v[40:43]
	v_mfma_f32_16x16x32_bf16 v[28:31], v[142:145], v[180:183], v[28:31]
	v_mfma_f32_16x16x32_bf16 v[24:27], v[156:159], v[180:183], v[24:27]
	v_mfma_f32_16x16x32_bf16 v[12:15], v[142:145], v[188:191], v[12:15]
	v_mfma_f32_16x16x32_bf16 v[8:11], v[156:159], v[188:191], v[8:11]
	v_mfma_f32_16x16x32_bf16 v[60:63], v[146:149], v[168:171], v[60:63]
	v_mfma_f32_16x16x32_bf16 v[56:59], v[160:163], v[168:171], v[56:59]
	v_mfma_f32_16x16x32_bf16 v[44:47], v[146:149], v[176:179], v[44:47]
	v_mfma_f32_16x16x32_bf16 v[40:43], v[160:163], v[176:179], v[40:43]
	v_mfma_f32_16x16x32_bf16 v[28:31], v[146:149], v[184:187], v[28:31]
	v_mfma_f32_16x16x32_bf16 v[24:27], v[160:163], v[184:187], v[24:27]
	v_mfma_f32_16x16x32_bf16 v[12:15], v[146:149], v[192:195], v[12:15]
	v_mfma_f32_16x16x32_bf16 v[8:11], v[160:163], v[192:195], v[8:11]
	s_setprio 0
.Lskp7_2:
	s_barrier
	s_add_u32 s50, s28, 0x40000
	s_addc_u32 s51, s29, 0
	s_add_i32 s49, s42, s1
	v_lshl_add_u64 v[142:143], s[50:51], 0, v[130:131]
	s_mov_b32 m0, s49
	s_nop 0
	global_load_lds_dwordx4 v[142:143], off
	v_lshl_add_u64 v[142:143], s[50:51], 0, v[134:135]
	s_add_i32 m0, s49, 0x2000
	s_nop 0
	global_load_lds_dwordx4 v[142:143], off
	s_waitcnt vmcnt(6)
	s_barrier
	s_cbranch_vccnz .Lskp7_3
	s_setprio 1
	v_mfma_f32_16x16x32_bf16 v[52:55], v[196:199], v[164:167], v[52:55]
	v_mfma_f32_16x16x32_bf16 v[48:51], v[204:207], v[164:167], v[48:51]
	v_mfma_f32_16x16x32_bf16 v[36:39], v[196:199], v[172:175], v[36:39]
	v_mfma_f32_16x16x32_bf16 v[32:35], v[204:207], v[172:175], v[32:35]
	v_mfma_f32_16x16x32_bf16 v[20:23], v[196:199], v[180:183], v[20:23]
	v_mfma_f32_16x16x32_bf16 v[16:19], v[204:207], v[180:183], v[16:19]
	v_mfma_f32_16x16x32_bf16 v[4:7], v[196:199], v[188:191], v[4:7]
	v_mfma_f32_16x16x32_bf16 v[0:3], v[204:207], v[188:191], v[0:3]
	v_mfma_f32_16x16x32_bf16 v[52:55], v[200:203], v[168:171], v[52:55]
	v_mfma_f32_16x16x32_bf16 v[48:51], v[208:211], v[168:171], v[48:51]
	v_mfma_f32_16x16x32_bf16 v[36:39], v[200:203], v[176:179], v[36:39]
	v_mfma_f32_16x16x32_bf16 v[32:35], v[208:211], v[176:179], v[32:35]
	v_mfma_f32_16x16x32_bf16 v[20:23], v[200:203], v[184:187], v[20:23]
	v_mfma_f32_16x16x32_bf16 v[16:19], v[208:211], v[184:187], v[16:19]
	v_mfma_f32_16x16x32_bf16 v[4:7], v[200:203], v[192:195], v[4:7]
	v_mfma_f32_16x16x32_bf16 v[0:3], v[208:211], v[192:195], v[0:3]
	s_setprio 0
; #define PG8_STAGE(bufoff, gbase, voff) do { _Pragma("unroll") for (int _i = 0; _i < 2; ++_i) \
;         __builtin_amdgcn_global_load_lds((const unsigned*)((const char*)(gbase) + (voff)[_i]), (LAS unsigned*)(lds + (bufoff) + ldsw + _i * 8192), 16, 0, 0); } while (0)
; #define PG8_LDA(dst, b, h) do { _Pragma("unroll") for (int m = 0; m < 4; ++m) _Pragma("unroll") for (int k = 0; k < 2; ++k) dst[m][k] = *(const LAS bf16x8*)(lds + PG8_SA(b, h) + aoff + m * 2048 + k * 1024); } while (0)
; #define PG8_LDB(dst, b, h) do { _Pragma("unroll") for (int n = 0; n < 2; ++n) _Pragma("unroll") for (int k = 0; k < 2; ++k) dst[n][k] = *(const LAS bf16x8*)(lds + PG8_SB(b, h) + boff + n * 2048 + k * 1024); } while (0)
; #define PG8_MMA(ai, bj, At, Bt) do { __builtin_amdgcn_s_setprio(1); _Pragma("unroll") for (int m = 0; m < 4; ++m) _Pragma("unroll") for (int n = 0; n < 2; ++n) _Pragma("unroll") for (int k = 0; k < 2; ++k) \
;         acc[ai][bj][m][n] = __builtin_amdgcn_mfma_f32_16x16x32_bf16(Bt[n][k], At[m][k], acc[ai][bj][m][n], 0, 0, 0); __builtin_amdgcn_s_setprio(0); } while (0)
; #define PG8_WAIT_L(n) asm volatile("s_waitcnt lgkmcnt(" #n ")" ::: "memory")
; #define PG8_BAR __builtin_amdgcn_s_barrier()
; #define PG8_SCHED __builtin_amdgcn_sched_barrier(0)
; template <class Epi, class Sched>
; __device__ __forceinline__ void gemm_phase(LAS unsigned char* lds, const int K, const Sched& S, const Epi& E) {
;     ...
;             PG8_LDB(B0, 1, 0); PG8_SCHED; PG8_LDA(At, 1, 0); PG8_STAGE(PG8_SA(0, 1), a2 + hstep, voffA);
;             PG8_WAIT_L(8); PG8_BAR; PG8_WAIT_L(0); PG8_MMA(0, 0, At, B0); PG8_BAR; PG8_SCHED;
;             PG8_LDB(B1, 1, 1); PG8_STAGE(PG8_SB(1, 0), b3, voffB);
;             PG8_BAR; PG8_WAIT_L(0); PG8_MMA(0, 1, At, B1); PG8_BAR;
;             PG8_LDA(At, 1, 1); PG8_STAGE(PG8_SA(1, 0), a3, voffA);
;             PG8_BAR; PG8_WAIT_L(0); PG8_MMA(1, 0, At, B0); PG8_BAR; PG8_SCHED;
.Lskp7_3:
	s_add_i32 s49, 0, 0x18000
	v_add_u32_e32 v160, s49, v151
	s_barrier
	ds_read_b128 v[142:145], v160
	ds_read_b128 v[146:149], v160 offset:1024
	ds_read_b128 v[156:159], v160 offset:2048
	ds_read_b128 v[160:163], v160 offset:3072
	s_add_u32 s30, s30, 0x40000
	s_addc_u32 s31, s31, 0
	s_mov_b32 m0, s36
	v_lshl_add_u64 v[196:197], s[30:31], 0, v[128:129]
	ds_read_b128 v[164:167], v153 offset:32768
	ds_read_b128 v[168:171], v153 offset:33792
	ds_read_b128 v[172:175], v153 offset:34816
	ds_read_b128 v[176:179], v153 offset:35840
	ds_read_b128 v[180:183], v153 offset:36864
	ds_read_b128 v[184:187], v153 offset:37888
	ds_read_b128 v[188:191], v153 offset:38912
	ds_read_b128 v[192:195], v153 offset:39936
	global_load_lds_dwordx4 v[196:197], off
	v_lshl_add_u64 v[196:197], s[30:31], 0, v[132:133]
	s_mov_b32 m0, s37
	s_nop 0
	global_load_lds_dwordx4 v[196:197], off
	s_waitcnt lgkmcnt(8)
	s_barrier
	s_waitcnt lgkmcnt(0)
	s_setprio 1
	s_waitcnt lgkmcnt(0)
	v_mfma_f32_16x16x32_bf16 v[124:127], v[142:145], v[164:167], v[124:127]
	v_mfma_f32_16x16x32_bf16 v[120:123], v[156:159], v[164:167], v[120:123]
	v_mfma_f32_16x16x32_bf16 v[108:111], v[142:145], v[172:175], v[108:111]
	v_mfma_f32_16x16x32_bf16 v[100:103], v[156:159], v[172:175], v[100:103]
	v_mfma_f32_16x16x32_bf16 v[92:95], v[142:145], v[180:183], v[92:95]
	v_mfma_f32_16x16x32_bf16 v[84:87], v[156:159], v[180:183], v[84:87]
	v_mfma_f32_16x16x32_bf16 v[76:79], v[142:145], v[188:191], v[76:79]
	v_mfma_f32_16x16x32_bf16 v[68:71], v[156:159], v[188:191], v[68:71]
	v_mfma_f32_16x16x32_bf16 v[124:127], v[146:149], v[168:171], v[124:127]
	v_mfma_f32_16x16x32_bf16 v[120:123], v[160:163], v[168:171], v[120:123]
	v_mfma_f32_16x16x32_bf16 v[108:111], v[146:149], v[176:179], v[108:111]
	v_mfma_f32_16x16x32_bf16 v[100:103], v[160:163], v[176:179], v[100:103]
	v_mfma_f32_16x16x32_bf16 v[92:95], v[146:149], v[184:187], v[92:95]
	v_mfma_f32_16x16x32_bf16 v[84:87], v[160:163], v[184:187], v[84:87]
	v_mfma_f32_16x16x32_bf16 v[76:79], v[146:149], v[192:195], v[76:79]
	v_mfma_f32_16x16x32_bf16 v[68:71], v[160:163], v[192:195], v[68:71]
	s_setprio 0
	s_barrier
	s_add_i32 s30, 0, 0x1c000
	s_add_i32 s31, s49, s1
	v_add_u32_e32 v208, s30, v151
	v_lshl_add_u64 v[212:213], v[212:213], 0, s[8:9]
	s_mov_b32 m0, s31
	ds_read_b128 v[196:199], v208
	ds_read_b128 v[200:203], v208 offset:1024
	ds_read_b128 v[204:207], v208 offset:2048
	ds_read_b128 v[208:211], v208 offset:3072
	global_load_lds_dwordx4 v[212:213], off
	v_lshl_add_u64 v[212:213], v[214:215], 0, s[8:9]
	s_add_i32 m0, s31, 0x2000
	s_nop 0
	global_load_lds_dwordx4 v[212:213], off
	s_barrier
	s_waitcnt lgkmcnt(0)
	s_setprio 1
	s_waitcnt lgkmcnt(0)
	v_mfma_f32_16x16x32_bf16 v[116:119], v[196:199], v[164:167], v[116:119]
	v_mfma_f32_16x16x32_bf16 v[112:115], v[204:207], v[164:167], v[112:115]
	v_mfma_f32_16x16x32_bf16 v[104:107], v[196:199], v[172:175], v[104:107]
	v_mfma_f32_16x16x32_bf16 v[96:99], v[204:207], v[172:175], v[96:99]
	v_mfma_f32_16x16x32_bf16 v[88:91], v[196:199], v[180:183], v[88:91]
	v_mfma_f32_16x16x32_bf16 v[80:83], v[204:207], v[180:183], v[80:83]
	v_mfma_f32_16x16x32_bf16 v[72:75], v[196:199], v[188:191], v[72:75]
	v_mfma_f32_16x16x32_bf16 v[64:67], v[204:207], v[188:191], v[64:67]
	v_mfma_f32_16x16x32_bf16 v[116:119], v[200:203], v[168:171], v[116:119]
	v_mfma_f32_16x16x32_bf16 v[112:115], v[208:211], v[168:171], v[112:115]
	v_mfma_f32_16x16x32_bf16 v[104:107], v[200:203], v[176:179], v[104:107]
	v_mfma_f32_16x16x32_bf16 v[96:99], v[208:211], v[176:179], v[96:99]
	v_mfma_f32_16x16x32_bf16 v[88:91], v[200:203], v[184:187], v[88:91]
	v_mfma_f32_16x16x32_bf16 v[80:83], v[208:211], v[184:187], v[80:83]
	v_mfma_f32_16x16x32_bf16 v[72:75], v[200:203], v[192:195], v[72:75]
	v_mfma_f32_16x16x32_bf16 v[64:67], v[208:211], v[192:195], v[64:67]
	s_setprio 0
	s_mov_b32 m0, s39
	v_lshl_add_u64 v[212:213], v[216:217], 0, s[8:9]
	s_barrier
	ds_read_b128 v[164:167], v153 offset:49152
	ds_read_b128 v[168:171], v153 offset:50176
	ds_read_b128 v[172:175], v153 offset:51200
	ds_read_b128 v[176:179], v153 offset:52224
	ds_read_b128 v[180:183], v153 offset:53248
	ds_read_b128 v[184:187], v153 offset:54272
	ds_read_b128 v[188:191], v153 offset:55296
	ds_read_b128 v[192:195], v153 offset:56320
	global_load_lds_dwordx4 v[212:213], off
	v_lshl_add_u64 v[212:213], v[218:219], 0, s[8:9]
	s_mov_b32 m0, s40
	s_nop 0
	global_load_lds_dwordx4 v[212:213], off
	s_barrier
	s_waitcnt lgkmcnt(0)
	s_cbranch_vccnz .Lskp7_6
	s_setprio 1
	s_waitcnt lgkmcnt(0)
	v_mfma_f32_16x16x32_bf16 v[60:63], v[142:145], v[164:167], v[60:63]
	v_mfma_f32_16x16x32_bf16 v[56:59], v[156:159], v[164:167], v[56:59]
	v_mfma_f32_16x16x32_bf16 v[44:47], v[142:145], v[172:175], v[44:47]
	v_mfma_f32_16x16x32_bf16 v[40:43], v[156:159], v[172:175], v[40:43]
	v_mfma_f32_16x16x32_bf16 v[28:31], v[142:145], v[180:183], v[28:31]
	v_mfma_f32_16x16x32_bf16 v[24:27], v[156:159], v[180:183], v[24:27]
	v_mfma_f32_16x16x32_bf16 v[12:15], v[142:145], v[188:191], v[12:15]
	v_mfma_f32_16x16x32_bf16 v[8:11], v[156:159], v[188:191], v[8:11]
	v_mfma_f32_16x16x32_bf16 v[60:63], v[146:149], v[168:171], v[60:63]
	v_mfma_f32_16x16x32_bf16 v[56:59], v[160:163], v[168:171], v[56:59]
	v_mfma_f32_16x16x32_bf16 v[44:47], v[146:149], v[176:179], v[44:47]
	v_mfma_f32_16x16x32_bf16 v[40:43], v[160:163], v[176:179], v[40:43]
	v_mfma_f32_16x16x32_bf16 v[28:31], v[146:149], v[184:187], v[28:31]
	v_mfma_f32_16x16x32_bf16 v[24:27], v[160:163], v[184:187], v[24:27]
	v_mfma_f32_16x16x32_bf16 v[12:15], v[146:149], v[192:195], v[12:15]
	v_mfma_f32_16x16x32_bf16 v[8:11], v[160:163], v[192:195], v[8:11]
	s_setprio 0
; __device__ __forceinline__ float sigmoidf_(float x) { return __builtin_amdgcn_rcpf(1.0f + __builtin_amdgcn_exp2f(-1.4426950408889634f * x)); }
; #define PG8_STAGE(bufoff, gbase, voff) do { _Pragma("unroll") for (int _i = 0; _i < 2; ++_i) \
;         __builtin_amdgcn_global_load_lds((const unsigned*)((const char*)(gbase) + (voff)[_i]), (LAS unsigned*)(lds + (bufoff) + ldsw + _i * 8192), 16, 0, 0); } while (0)
; #define PG8_MMA(ai, bj, At, Bt) do { __builtin_amdgcn_s_setprio(1); _Pragma("unroll") for (int m = 0; m < 4; ++m) _Pragma("unroll") for (int n = 0; n < 2; ++n) _Pragma("unroll") for (int k = 0; k < 2; ++k) \
;         acc[ai][bj][m][n] = __builtin_amdgcn_mfma_f32_16x16x32_bf16(Bt[n][k], At[m][k], acc[ai][bj][m][n], 0, 0, 0); __builtin_amdgcn_s_setprio(0); } while (0)
; #define PG8_WAIT_V(n) asm volatile("s_waitcnt vmcnt(" #n ")" ::: "memory")
; #define PG8_BAR __builtin_amdgcn_s_barrier()
; template <class Epi, class Sched>
; __device__ __forceinline__ void gemm_phase(LAS unsigned char* lds, const int K, const Sched& S, const Epi& E) {
;     ...
;             PG8_STAGE(PG8_SB(1, 1), b3 + hstep, voffB);
;             PG8_WAIT_V(6); PG8_BAR; PG8_MMA(1, 1, At, B1); PG8_BAR;
;     __device__ __forceinline__ void operator()(Acc& acc, const Unit& u, int wr, int wc, int fr, int fq) const {
;     ...
;             bf16_t* O = (bf16_t*)(ws + R_A); const float* ssq = (const float*)(ws + W_SSQ2);
;             float rsv[2][4];
; #pragma unroll
;             for (int ai = 0; ai < 2; ++ai)
; #pragma unroll
;                 for (int m = 0; m < 4; ++m) rsv[ai][m] = ssq[row0 + ai * 128 + m * 16];
; #pragma unroll
;             for (int ai = 0; ai < 2; ++ai)
; #pragma unroll
;                 for (int m = 0; m < 4; ++m) { const int R = row0 + ai * 128 + m * 16;
;                     const float rs = __builtin_amdgcn_rsqf(rsv[ai][m] * (1.0f / 1024.0f) + EPS);
;                     f32x4 o[2];
; #pragma unroll
;                     for (int n = 0; n < 2; ++n)
; #pragma unroll
;                         for (int j = 0; j < 4; ++j) { const float g = acc[ai][0][m][n][j] * rs, up = acc[ai][1][m][n][j] * rs; o[n][j] = g * sigmoidf_(g) * up; }
;                     *(u32x4*)(O + (size_t)R * DFF + u.pn * 128 + cl0) = pack8(o[0], o[1]); }
.Lskp7_6:
	s_barrier
	s_add_u32 s28, s28, 0x40080
	s_addc_u32 s29, s29, 0
	s_add_i32 s30, s30, s1
	v_lshl_add_u64 v[142:143], s[28:29], 0, v[130:131]
	s_mov_b32 m0, s30
	s_nop 0
	global_load_lds_dwordx4 v[142:143], off
	v_lshl_add_u64 v[142:143], s[28:29], 0, v[134:135]
	s_add_i32 m0, s30, 0x2000
	s_nop 0
	global_load_lds_dwordx4 v[142:143], off
	s_waitcnt vmcnt(6)
	s_barrier
	s_cbranch_vccnz .Lskp7_7
	s_setprio 1
	v_mfma_f32_16x16x32_bf16 v[52:55], v[196:199], v[164:167], v[52:55]
	v_mfma_f32_16x16x32_bf16 v[48:51], v[204:207], v[164:167], v[48:51]
	v_mfma_f32_16x16x32_bf16 v[36:39], v[196:199], v[172:175], v[36:39]
	v_mfma_f32_16x16x32_bf16 v[32:35], v[204:207], v[172:175], v[32:35]
	v_mfma_f32_16x16x32_bf16 v[20:23], v[196:199], v[180:183], v[20:23]
	v_mfma_f32_16x16x32_bf16 v[16:19], v[204:207], v[180:183], v[16:19]
	v_mfma_f32_16x16x32_bf16 v[4:7], v[196:199], v[188:191], v[4:7]
	v_mfma_f32_16x16x32_bf16 v[0:3], v[204:207], v[188:191], v[0:3]
	v_mfma_f32_16x16x32_bf16 v[52:55], v[200:203], v[168:171], v[52:55]
	v_mfma_f32_16x16x32_bf16 v[48:51], v[208:211], v[168:171], v[48:51]
	v_mfma_f32_16x16x32_bf16 v[36:39], v[200:203], v[176:179], v[36:39]
	v_mfma_f32_16x16x32_bf16 v[32:35], v[208:211], v[176:179], v[32:35]
	v_mfma_f32_16x16x32_bf16 v[20:23], v[200:203], v[184:187], v[20:23]
	v_mfma_f32_16x16x32_bf16 v[16:19], v[208:211], v[184:187], v[16:19]
	v_mfma_f32_16x16x32_bf16 v[4:7], v[200:203], v[192:195], v[4:7]
	v_mfma_f32_16x16x32_bf16 v[0:3], v[208:211], v[192:195], v[0:3]
	s_setprio 0
.Lskp7_7:
	s_add_i32 s48, s48, 2
	s_add_u32 s26, s26, 0x100
	s_addc_u32 s27, s27, 0
	s_add_u32 s46, s46, 0x100
	s_addc_u32 s47, s47, 0
	s_cmp_gt_u32 s48, 13
	s_barrier
	s_cbranch_scc0 .LBB0_1371
	v_lshl_add_u32 v158, s24, 8, v150
	v_ashrrev_i32_e32 v159, 31, v158
	v_lshl_add_u64 v[160:161], v[158:159], 2, s[10:11]
	v_or_b32_e32 v146, 16, v158
	v_mov_b32_e32 v166, v232
	v_ashrrev_i32_e32 v147, 31, v146
	v_lshl_add_u64 v[142:143], v[146:147], 2, s[10:11]
	v_mov_b32_e32 v167, v233
	v_or_b32_e32 v148, 32, v158
	v_or_b32_e32 v144, 48, v158
	v_ashrrev_i32_e32 v149, 31, v148
	v_ashrrev_i32_e32 v145, 31, v144
	v_lshl_add_u64 v[162:163], v[148:149], 2, s[10:11]
	v_lshl_add_u64 v[164:165], v[144:145], 2, s[10:11]
	v_mov_b32_e32 v173, v236
	v_mov_b32_e32 v174, v237
	v_mov_b32_e32 v149, v238
	s_nop 0
	v_mov_b32_e32 v163, v234
	s_nop 0
	v_mov_b32_e32 v175, v235
	v_mov_b32_e32 v145, v239
	s_lshl_b32 s24, s25, 7
	v_mov_b64_e32 v[142:143], s[12:13]
	s_ashr_i32 s25, s24, 31
	v_add_u32_e32 v172, 0x80, v158
	v_add_u32_e32 v157, 0x90, v158
	v_add_u32_e32 v156, 0xa0, v158
	v_add_u32_e32 v147, 0xb0, v158
	v_mad_i64_i32 v[158:159], s[26:27], v158, s43, v[142:143]
	s_lshl_b64 s[24:25], s[24:25], 1
	v_lshl_add_u64 v[158:159], v[158:159], 0, s[24:25]
	v_lshl_add_u64 v[158:159], v[158:159], 0, v[136:137]
	s_and_b64 vcc, exec, s[14:15]
	s_mov_b64 s[28:29], s[22:23]
	v_fmamk_f32 v160, v166, 0x3a800000, v155
	v_rsq_f32_e32 v160, v160
	v_fmamk_f32 v161, v167, 0x3a800000, v155
	v_rsq_f32_e32 v162, v161
	v_pk_mul_f32 v[124:125], v[124:125], v[160:161] op_sel_hi:[1,0]
	v_pk_mul_f32 v[126:127], v[126:127], v[160:161] op_sel_hi:[1,0]
	v_pk_mul_f32 v[120:121], v[120:121], v[160:161] op_sel_hi:[1,0]
	v_pk_mul_f32 v[122:123], v[122:123], v[160:161] op_sel_hi:[1,0]
	v_mul_f32_e32 v166, 0xbfb8aa3b, v124
	v_mul_f32_e32 v167, 0xbfb8aa3b, v125
	v_mul_f32_e32 v168, 0xbfb8aa3b, v126
	v_mul_f32_e32 v169, 0xbfb8aa3b, v127
	v_mul_f32_e32 v170, 0xbfb8aa3b, v120
	v_mul_f32_e32 v171, 0xbfb8aa3b, v121
	v_mul_f32_e32 v176, 0xbfb8aa3b, v122
	v_mul_f32_e32 v177, 0xbfb8aa3b, v123
	v_pk_mul_f32 v[116:117], v[116:117], v[160:161] op_sel_hi:[1,0]
	v_pk_mul_f32 v[118:119], v[118:119], v[160:161] op_sel_hi:[1,0]
	v_pk_mul_f32 v[112:113], v[112:113], v[160:161] op_sel_hi:[1,0]
	v_pk_mul_f32 v[114:115], v[114:115], v[160:161] op_sel_hi:[1,0]
	v_pk_mul_f32 v[160:161], v[108:109], v[162:163] op_sel_hi:[1,0]
	v_pk_mul_f32 v[164:165], v[110:111], v[162:163] op_sel_hi:[1,0]
	v_exp_f32_e32 v108, v166
	v_exp_f32_e32 v109, v167
	v_exp_f32_e32 v110, v168
	v_exp_f32_e32 v111, v169
	v_exp_f32_e32 v166, v170
	v_exp_f32_e32 v167, v171
	v_exp_f32_e32 v168, v176
	v_exp_f32_e32 v169, v177
	v_add_f32_e32 v108, 1.0, v108
	v_add_f32_e32 v109, 1.0, v109
	v_add_f32_e32 v110, 1.0, v110
	v_add_f32_e32 v111, 1.0, v111
	v_add_f32_e32 v166, 1.0, v166
	v_add_f32_e32 v167, 1.0, v167
	v_add_f32_e32 v168, 1.0, v168
	v_add_f32_e32 v169, 1.0, v169
	v_rcp_f32_e32 v108, v108
	v_rcp_f32_e32 v109, v109
	v_rcp_f32_e32 v110, v110
	v_rcp_f32_e32 v111, v111
	v_rcp_f32_e32 v166, v166
	v_rcp_f32_e32 v167, v167
	v_rcp_f32_e32 v168, v168
	v_rcp_f32_e32 v169, v169
	v_pk_mul_f32 v[108:109], v[124:125], v[108:109]
	v_pk_mul_f32 v[110:111], v[126:127], v[110:111]
	v_pk_mul_f32 v[120:121], v[120:121], v[166:167]
	v_pk_mul_f32 v[122:123], v[122:123], v[168:169]
	v_mul_f32_e32 v170, 0xbfb8aa3b, v160
	v_mul_f32_e32 v171, 0xbfb8aa3b, v161
	v_pk_mul_f32 v[108:109], v[116:117], v[108:109]
	v_pk_mul_f32 v[110:111], v[118:119], v[110:111]
	v_pk_mul_f32 v[112:113], v[112:113], v[120:121]
	v_pk_mul_f32 v[114:115], v[114:115], v[122:123]
	v_mul_f32_e32 v176, 0xbfb8aa3b, v164
	v_mul_f32_e32 v177, 0xbfb8aa3b, v165
	v_exp_f32_e32 v170, v170
	v_exp_f32_e32 v171, v171
	v_cvt_pk_bf16_f32 v108, v108, v109
	v_cvt_pk_bf16_f32 v109, v110, v111
	v_cvt_pk_bf16_f32 v110, v112, v113
	v_cvt_pk_bf16_f32 v111, v114, v115
	v_exp_f32_e32 v176, v176
	global_store_dwordx4 v[158:159], v[108:111], off
	v_add_f32_e32 v170, 1.0, v170
	v_add_f32_e32 v171, 1.0, v171
	v_exp_f32_e32 v111, v177
	v_rcp_f32_e32 v170, v170
	v_rcp_f32_e32 v171, v171
	v_add_f32_e32 v110, 1.0, v176
	v_add_f32_e32 v111, 1.0, v111
; __device__ __forceinline__ float sigmoidf_(float x) { return __builtin_amdgcn_rcpf(1.0f + __builtin_amdgcn_exp2f(-1.4426950408889634f * x)); }
; __device__ __forceinline__ u32x4 pack8(f32x4 a, f32x4 b) { u32x4 w; w.x = pk2(a[0], a[1]); w.y = pk2(a[2], a[3]); w.z = pk2(b[0], b[1]); w.w = pk2(b[2], b[3]); return w; }
;     __device__ __forceinline__ void operator()(Acc& acc, const Unit& u, int wr, int wc, int fr, int fq) const {
;     ...
;             for (int ai = 0; ai < 2; ++ai)
; #pragma unroll
;                 for (int m = 0; m < 4; ++m) { const int R = row0 + ai * 128 + m * 16;
;                     const float rs = __builtin_amdgcn_rsqf(rsv[ai][m] * (1.0f / 1024.0f) + EPS);
;                     f32x4 o[2];
; #pragma unroll
;                     for (int n = 0; n < 2; ++n)
; #pragma unroll
;                         for (int j = 0; j < 4; ++j) { const float g = acc[ai][0][m][n][j] * rs, up = acc[ai][1][m][n][j] * rs; o[n][j] = g * sigmoidf_(g) * up; }
;                     *(u32x4*)(O + (size_t)R * DFF + u.pn * 128 + cl0) = pack8(o[0], o[1]); }
	v_rcp_f32_e32 v110, v110
	v_rcp_f32_e32 v111, v111
	v_pk_mul_f32 v[104:105], v[104:105], v[162:163] op_sel_hi:[1,0]
	v_pk_mul_f32 v[108:109], v[160:161], v[170:171]
	v_pk_mul_f32 v[106:107], v[106:107], v[162:163] op_sel_hi:[1,0]
	v_pk_mul_f32 v[104:105], v[104:105], v[108:109]
	v_pk_mul_f32 v[108:109], v[164:165], v[110:111]
	v_pk_mul_f32 v[100:101], v[100:101], v[162:163] op_sel_hi:[1,0]
	v_cvt_pk_bf16_f32 v104, v104, v105
	v_pk_mul_f32 v[106:107], v[106:107], v[108:109]
	v_mul_f32_e32 v105, 0xbfb8aa3b, v100
	v_exp_f32_e32 v108, v105
	v_cvt_pk_bf16_f32 v105, v106, v107
	v_mul_f32_e32 v106, 0xbfb8aa3b, v101
	v_exp_f32_e32 v107, v106
	v_pk_mul_f32 v[102:103], v[102:103], v[162:163] op_sel_hi:[1,0]
	v_add_f32_e32 v106, 1.0, v108
	v_mul_f32_e32 v108, 0xbfb8aa3b, v102
	v_add_f32_e32 v107, 1.0, v107
	v_rcp_f32_e32 v106, v106
	v_rcp_f32_e32 v107, v107
	v_exp_f32_e32 v108, v108
	v_mul_f32_e32 v109, 0xbfb8aa3b, v103
	v_exp_f32_e32 v109, v109
	v_pk_mul_f32 v[100:101], v[100:101], v[106:107]
	v_add_f32_e32 v106, 1.0, v108
	v_rcp_f32_e32 v108, v106
	v_add_f32_e32 v106, 1.0, v109
	v_rcp_f32_e32 v109, v106
	v_pk_mul_f32 v[96:97], v[96:97], v[162:163] op_sel_hi:[1,0]
	s_nop 0
	v_pk_mul_f32 v[96:97], v[96:97], v[100:101]
	s_nop 0
	v_cvt_pk_bf16_f32 v106, v96, v97
	v_pk_mul_f32 v[96:97], v[98:99], v[162:163] op_sel_hi:[1,0]
	v_pk_mul_f32 v[98:99], v[102:103], v[108:109]
	s_nop 0
	v_pk_mul_f32 v[96:97], v[96:97], v[98:99]
	v_mad_i64_i32 v[98:99], s[26:27], v146, s43, v[142:143]
	v_cvt_pk_bf16_f32 v107, v96, v97
	v_fmamk_f32 v96, v163, 0x3a800000, v155
	v_rsq_f32_e32 v96, v96
	v_lshl_add_u64 v[98:99], v[98:99], 0, s[24:25]
	v_lshl_add_u64 v[98:99], v[98:99], 0, v[136:137]
	global_store_dwordx4 v[98:99], v[104:107], off
	v_pk_mul_f32 v[92:93], v[92:93], v[96:97] op_sel_hi:[1,0]
	s_nop 0
	v_mul_f32_e32 v97, 0xbfb8aa3b, v92
	v_exp_f32_e32 v97, v97
	v_mul_f32_e32 v98, 0xbfb8aa3b, v93
	v_exp_f32_e32 v99, v98
	v_add_f32_e32 v97, 1.0, v97
	v_rcp_f32_e32 v98, v97
	v_pk_mul_f32 v[88:89], v[88:89], v[96:97] op_sel_hi:[1,0]
	v_add_f32_e32 v97, 1.0, v99
	v_pk_mul_f32 v[94:95], v[94:95], v[96:97] op_sel_hi:[1,0]
	v_rcp_f32_e32 v99, v97
	v_mul_f32_e32 v97, 0xbfb8aa3b, v94
	v_exp_f32_e32 v97, v97
	v_mul_f32_e32 v100, 0xbfb8aa3b, v95
	v_exp_f32_e32 v100, v100
	v_pk_mul_f32 v[92:93], v[92:93], v[98:99]
	v_add_f32_e32 v97, 1.0, v97
	v_rcp_f32_e32 v98, v97
	v_add_f32_e32 v97, 1.0, v100
	v_rcp_f32_e32 v99, v97
	v_pk_mul_f32 v[88:89], v[88:89], v[92:93]
	v_pk_mul_f32 v[90:91], v[90:91], v[96:97] op_sel_hi:[1,0]
	v_pk_mul_f32 v[84:85], v[84:85], v[96:97] op_sel_hi:[1,0]
	v_pk_mul_f32 v[92:93], v[94:95], v[98:99]
	v_cvt_pk_bf16_f32 v88, v88, v89
	v_pk_mul_f32 v[90:91], v[90:91], v[92:93]
	v_mul_f32_e32 v89, 0xbfb8aa3b, v84
	v_exp_f32_e32 v92, v89
	v_cvt_pk_bf16_f32 v89, v90, v91
	v_mul_f32_e32 v90, 0xbfb8aa3b, v85
	v_exp_f32_e32 v91, v90
	v_pk_mul_f32 v[86:87], v[86:87], v[96:97] op_sel_hi:[1,0]
	v_add_f32_e32 v90, 1.0, v92
	v_mul_f32_e32 v92, 0xbfb8aa3b, v86
	v_add_f32_e32 v91, 1.0, v91
	v_rcp_f32_e32 v90, v90
	v_rcp_f32_e32 v91, v91
	v_exp_f32_e32 v92, v92
	v_mul_f32_e32 v93, 0xbfb8aa3b, v87
	v_exp_f32_e32 v93, v93
	v_pk_mul_f32 v[84:85], v[84:85], v[90:91]
	v_add_f32_e32 v90, 1.0, v92
	v_rcp_f32_e32 v92, v90
	v_add_f32_e32 v90, 1.0, v93
	v_rcp_f32_e32 v93, v90
	v_pk_mul_f32 v[80:81], v[80:81], v[96:97] op_sel_hi:[1,0]
	s_nop 0
	v_pk_mul_f32 v[80:81], v[80:81], v[84:85]
	s_nop 0
	v_cvt_pk_bf16_f32 v90, v80, v81
	v_pk_mul_f32 v[80:81], v[82:83], v[96:97] op_sel_hi:[1,0]
	v_pk_mul_f32 v[82:83], v[86:87], v[92:93]
	s_nop 0
	v_pk_mul_f32 v[80:81], v[80:81], v[82:83]
	v_mad_i64_i32 v[82:83], s[26:27], v148, s43, v[142:143]
	v_cvt_pk_bf16_f32 v91, v80, v81
	v_fmamk_f32 v80, v175, 0x3a800000, v155
	v_rsq_f32_e32 v80, v80
	v_lshl_add_u64 v[82:83], v[82:83], 0, s[24:25]
	v_lshl_add_u64 v[82:83], v[82:83], 0, v[136:137]
	global_store_dwordx4 v[82:83], v[88:91], off
	v_pk_mul_f32 v[76:77], v[76:77], v[80:81] op_sel_hi:[1,0]
	s_nop 0
	v_mul_f32_e32 v81, 0xbfb8aa3b, v76
	v_exp_f32_e32 v81, v81
	v_mul_f32_e32 v82, 0xbfb8aa3b, v77
	v_exp_f32_e32 v83, v82
	v_add_f32_e32 v81, 1.0, v81
	v_rcp_f32_e32 v82, v81
	v_pk_mul_f32 v[72:73], v[72:73], v[80:81] op_sel_hi:[1,0]
	v_add_f32_e32 v81, 1.0, v83
	v_pk_mul_f32 v[78:79], v[78:79], v[80:81] op_sel_hi:[1,0]
	v_rcp_f32_e32 v83, v81
	v_mul_f32_e32 v81, 0xbfb8aa3b, v78
	v_exp_f32_e32 v81, v81
	v_mul_f32_e32 v84, 0xbfb8aa3b, v79
	v_exp_f32_e32 v84, v84
	v_pk_mul_f32 v[76:77], v[76:77], v[82:83]
	v_add_f32_e32 v81, 1.0, v81
	v_rcp_f32_e32 v82, v81
	v_add_f32_e32 v81, 1.0, v84
	v_rcp_f32_e32 v83, v81
	v_pk_mul_f32 v[72:73], v[72:73], v[76:77]
	v_pk_mul_f32 v[74:75], v[74:75], v[80:81] op_sel_hi:[1,0]
	v_pk_mul_f32 v[68:69], v[68:69], v[80:81] op_sel_hi:[1,0]
	v_pk_mul_f32 v[76:77], v[78:79], v[82:83]
	v_cvt_pk_bf16_f32 v72, v72, v73
	v_pk_mul_f32 v[74:75], v[74:75], v[76:77]
	v_mul_f32_e32 v73, 0xbfb8aa3b, v68
	v_exp_f32_e32 v76, v73
	v_cvt_pk_bf16_f32 v73, v74, v75
	v_mul_f32_e32 v74, 0xbfb8aa3b, v69
	v_exp_f32_e32 v75, v74
	v_pk_mul_f32 v[70:71], v[70:71], v[80:81] op_sel_hi:[1,0]
	v_add_f32_e32 v74, 1.0, v76
	v_mul_f32_e32 v76, 0xbfb8aa3b, v70
	v_add_f32_e32 v75, 1.0, v75
	v_rcp_f32_e32 v74, v74
	v_rcp_f32_e32 v75, v75
	v_exp_f32_e32 v76, v76
	v_mul_f32_e32 v77, 0xbfb8aa3b, v71
	v_exp_f32_e32 v77, v77
	v_pk_mul_f32 v[68:69], v[68:69], v[74:75]
	v_add_f32_e32 v74, 1.0, v76
	v_rcp_f32_e32 v76, v74
	v_add_f32_e32 v74, 1.0, v77
	v_rcp_f32_e32 v77, v74
	v_pk_mul_f32 v[64:65], v[64:65], v[80:81] op_sel_hi:[1,0]
	s_nop 0
	v_pk_mul_f32 v[64:65], v[64:65], v[68:69]
	s_nop 0
	v_cvt_pk_bf16_f32 v74, v64, v65
	v_pk_mul_f32 v[64:65], v[66:67], v[80:81] op_sel_hi:[1,0]
; __device__ __forceinline__ float sigmoidf_(float x) { return __builtin_amdgcn_rcpf(1.0f + __builtin_amdgcn_exp2f(-1.4426950408889634f * x)); }
; __device__ __forceinline__ u32x4 pack8(f32x4 a, f32x4 b) { u32x4 w; w.x = pk2(a[0], a[1]); w.y = pk2(a[2], a[3]); w.z = pk2(b[0], b[1]); w.w = pk2(b[2], b[3]); return w; }
;     __device__ __forceinline__ void operator()(Acc& acc, const Unit& u, int wr, int wc, int fr, int fq) const {
;     ...
;             for (int ai = 0; ai < 2; ++ai)
; #pragma unroll
;                 for (int m = 0; m < 4; ++m) { const int R = row0 + ai * 128 + m * 16;
;                     const float rs = __builtin_amdgcn_rsqf(rsv[ai][m] * (1.0f / 1024.0f) + EPS);
;                     f32x4 o[2];
; #pragma unroll
;                     for (int n = 0; n < 2; ++n)
; #pragma unroll
;                         for (int j = 0; j < 4; ++j) { const float g = acc[ai][0][m][n][j] * rs, up = acc[ai][1][m][n][j] * rs; o[n][j] = g * sigmoidf_(g) * up; }
;                     *(u32x4*)(O + (size_t)R * DFF + u.pn * 128 + cl0) = pack8(o[0], o[1]); }
	v_pk_mul_f32 v[66:67], v[70:71], v[76:77]
	s_nop 0
	v_pk_mul_f32 v[64:65], v[64:65], v[66:67]
	v_mad_i64_i32 v[66:67], s[26:27], v144, s43, v[142:143]
	v_cvt_pk_bf16_f32 v75, v64, v65
	v_fmamk_f32 v64, v173, 0x3a800000, v155
	v_rsq_f32_e32 v64, v64
	v_lshl_add_u64 v[66:67], v[66:67], 0, s[24:25]
	v_lshl_add_u64 v[66:67], v[66:67], 0, v[136:137]
	global_store_dwordx4 v[66:67], v[72:75], off
	v_pk_mul_f32 v[60:61], v[60:61], v[64:65] op_sel_hi:[1,0]
	s_nop 0
	v_mul_f32_e32 v65, 0xbfb8aa3b, v60
	v_exp_f32_e32 v65, v65
	v_mul_f32_e32 v66, 0xbfb8aa3b, v61
	v_exp_f32_e32 v67, v66
	v_add_f32_e32 v65, 1.0, v65
	v_rcp_f32_e32 v66, v65
	v_pk_mul_f32 v[52:53], v[52:53], v[64:65] op_sel_hi:[1,0]
	v_add_f32_e32 v65, 1.0, v67
	v_pk_mul_f32 v[62:63], v[62:63], v[64:65] op_sel_hi:[1,0]
	v_rcp_f32_e32 v67, v65
	v_mul_f32_e32 v65, 0xbfb8aa3b, v62
	v_exp_f32_e32 v65, v65
	v_mul_f32_e32 v68, 0xbfb8aa3b, v63
	v_exp_f32_e32 v68, v68
	v_pk_mul_f32 v[60:61], v[60:61], v[66:67]
	v_add_f32_e32 v65, 1.0, v65
	v_rcp_f32_e32 v66, v65
	v_add_f32_e32 v65, 1.0, v68
	v_rcp_f32_e32 v67, v65
	v_pk_mul_f32 v[52:53], v[52:53], v[60:61]
	v_pk_mul_f32 v[54:55], v[54:55], v[64:65] op_sel_hi:[1,0]
	v_pk_mul_f32 v[56:57], v[56:57], v[64:65] op_sel_hi:[1,0]
	v_pk_mul_f32 v[60:61], v[62:63], v[66:67]
	v_cvt_pk_bf16_f32 v52, v52, v53
	v_pk_mul_f32 v[54:55], v[54:55], v[60:61]
	v_mul_f32_e32 v53, 0xbfb8aa3b, v56
	v_exp_f32_e32 v60, v53
	v_cvt_pk_bf16_f32 v53, v54, v55
	v_mul_f32_e32 v54, 0xbfb8aa3b, v57
	v_exp_f32_e32 v55, v54
	v_pk_mul_f32 v[58:59], v[58:59], v[64:65] op_sel_hi:[1,0]
	v_add_f32_e32 v54, 1.0, v60
	v_mul_f32_e32 v60, 0xbfb8aa3b, v58
	v_add_f32_e32 v55, 1.0, v55
	v_mul_f32_e32 v61, 0xbfb8aa3b, v59
	v_rcp_f32_e32 v54, v54
	v_rcp_f32_e32 v55, v55
	v_exp_f32_e32 v60, v60
	v_exp_f32_e32 v61, v61
	v_pk_mul_f32 v[48:49], v[48:49], v[64:65] op_sel_hi:[1,0]
	v_pk_mul_f32 v[54:55], v[56:57], v[54:55]
	v_add_f32_e32 v56, 1.0, v60
	v_add_f32_e32 v57, 1.0, v61
	v_rcp_f32_e32 v56, v56
	v_rcp_f32_e32 v57, v57
	v_pk_mul_f32 v[48:49], v[48:49], v[54:55]
	s_nop 0
	v_cvt_pk_bf16_f32 v54, v48, v49
	v_pk_mul_f32 v[48:49], v[50:51], v[64:65] op_sel_hi:[1,0]
	v_pk_mul_f32 v[50:51], v[58:59], v[56:57]
	s_nop 0
	v_pk_mul_f32 v[48:49], v[48:49], v[50:51]
	v_mad_i64_i32 v[50:51], s[26:27], v172, s43, v[142:143]
	v_cvt_pk_bf16_f32 v55, v48, v49
	v_fmamk_f32 v48, v174, 0x3a800000, v155
	v_rsq_f32_e32 v48, v48
	v_lshl_add_u64 v[50:51], v[50:51], 0, s[24:25]
	v_lshl_add_u64 v[50:51], v[50:51], 0, v[136:137]
	global_store_dwordx4 v[50:51], v[52:55], off
	v_pk_mul_f32 v[44:45], v[44:45], v[48:49] op_sel_hi:[1,0]
	s_nop 0
	v_mul_f32_e32 v49, 0xbfb8aa3b, v44
	v_exp_f32_e32 v49, v49
	v_mul_f32_e32 v50, 0xbfb8aa3b, v45
	v_exp_f32_e32 v51, v50
	v_add_f32_e32 v49, 1.0, v49
	v_rcp_f32_e32 v50, v49
	v_pk_mul_f32 v[36:37], v[36:37], v[48:49] op_sel_hi:[1,0]
	v_add_f32_e32 v49, 1.0, v51
	v_pk_mul_f32 v[46:47], v[46:47], v[48:49] op_sel_hi:[1,0]
	v_rcp_f32_e32 v51, v49
	v_mul_f32_e32 v49, 0xbfb8aa3b, v46
	v_exp_f32_e32 v49, v49
	v_mul_f32_e32 v52, 0xbfb8aa3b, v47
	v_exp_f32_e32 v52, v52
	v_pk_mul_f32 v[44:45], v[44:45], v[50:51]
	v_add_f32_e32 v49, 1.0, v49
	v_rcp_f32_e32 v50, v49
	v_add_f32_e32 v49, 1.0, v52
	v_rcp_f32_e32 v51, v49
	v_pk_mul_f32 v[36:37], v[36:37], v[44:45]
	v_pk_mul_f32 v[38:39], v[38:39], v[48:49] op_sel_hi:[1,0]
	v_pk_mul_f32 v[40:41], v[40:41], v[48:49] op_sel_hi:[1,0]
	v_pk_mul_f32 v[44:45], v[46:47], v[50:51]
	v_cvt_pk_bf16_f32 v36, v36, v37
	v_pk_mul_f32 v[38:39], v[38:39], v[44:45]
	v_mul_f32_e32 v37, 0xbfb8aa3b, v40
	v_exp_f32_e32 v44, v37
	v_cvt_pk_bf16_f32 v37, v38, v39
	v_mul_f32_e32 v38, 0xbfb8aa3b, v41
	v_exp_f32_e32 v39, v38
	v_pk_mul_f32 v[42:43], v[42:43], v[48:49] op_sel_hi:[1,0]
	v_add_f32_e32 v38, 1.0, v44
	v_mul_f32_e32 v44, 0xbfb8aa3b, v42
	v_add_f32_e32 v39, 1.0, v39
	v_mul_f32_e32 v45, 0xbfb8aa3b, v43
	v_rcp_f32_e32 v38, v38
	v_rcp_f32_e32 v39, v39
	v_exp_f32_e32 v44, v44
	v_exp_f32_e32 v45, v45
	v_pk_mul_f32 v[32:33], v[32:33], v[48:49] op_sel_hi:[1,0]
	v_pk_mul_f32 v[38:39], v[40:41], v[38:39]
	v_add_f32_e32 v40, 1.0, v44
	v_add_f32_e32 v41, 1.0, v45
	v_rcp_f32_e32 v40, v40
	v_rcp_f32_e32 v41, v41
	v_pk_mul_f32 v[32:33], v[32:33], v[38:39]
	s_nop 0
	v_cvt_pk_bf16_f32 v38, v32, v33
	v_pk_mul_f32 v[32:33], v[34:35], v[48:49] op_sel_hi:[1,0]
	v_pk_mul_f32 v[34:35], v[42:43], v[40:41]
	s_nop 0
	v_pk_mul_f32 v[32:33], v[32:33], v[34:35]
	v_mad_i64_i32 v[34:35], s[26:27], v157, s43, v[142:143]
	v_cvt_pk_bf16_f32 v39, v32, v33
	v_fmamk_f32 v32, v149, 0x3a800000, v155
; __device__ __forceinline__ float sigmoidf_(float x) { return __builtin_amdgcn_rcpf(1.0f + __builtin_amdgcn_exp2f(-1.4426950408889634f * x)); }
; #define PG8_WAIT_V(n) asm volatile("s_waitcnt vmcnt(" #n ")" ::: "memory")
; #define PG8_BAR __builtin_amdgcn_s_barrier()
; __device__ __forceinline__ u32x4 pack8(f32x4 a, f32x4 b) { u32x4 w; w.x = pk2(a[0], a[1]); w.y = pk2(a[2], a[3]); w.z = pk2(b[0], b[1]); w.w = pk2(b[2], b[3]); return w; }
; template <class Epi, class Sched>
; __device__ __forceinline__ void gemm_phase(LAS unsigned char* lds, const int K, const Sched& S, const Epi& E) {
;     ...
;         cur = nxt; cA = nA; cB = nB; ++ui;
;     }
;     PG8_WAIT_V(0);
;     if (wr == 0) PG8_BAR;
;     PG8_BAR;
;     __device__ __forceinline__ void operator()(Acc& acc, const Unit& u, int wr, int wc, int fr, int fq) const {
;     ...
;             for (int ai = 0; ai < 2; ++ai)
; #pragma unroll
;                 for (int m = 0; m < 4; ++m) { const int R = row0 + ai * 128 + m * 16;
;                     const float rs = __builtin_amdgcn_rsqf(rsv[ai][m] * (1.0f / 1024.0f) + EPS);
;                     f32x4 o[2];
; #pragma unroll
;                     for (int n = 0; n < 2; ++n)
; #pragma unroll
;                         for (int j = 0; j < 4; ++j) { const float g = acc[ai][0][m][n][j] * rs, up = acc[ai][1][m][n][j] * rs; o[n][j] = g * sigmoidf_(g) * up; }
;                     *(u32x4*)(O + (size_t)R * DFF + u.pn * 128 + cl0) = pack8(o[0], o[1]); }
	v_rsq_f32_e32 v32, v32
	v_lshl_add_u64 v[34:35], v[34:35], 0, s[24:25]
	v_lshl_add_u64 v[34:35], v[34:35], 0, v[136:137]
	global_store_dwordx4 v[34:35], v[36:39], off
	v_pk_mul_f32 v[28:29], v[28:29], v[32:33] op_sel_hi:[1,0]
	s_nop 0
	v_mul_f32_e32 v33, 0xbfb8aa3b, v28
	v_exp_f32_e32 v33, v33
	v_mul_f32_e32 v34, 0xbfb8aa3b, v29
	v_exp_f32_e32 v35, v34
	v_add_f32_e32 v33, 1.0, v33
	v_rcp_f32_e32 v34, v33
	v_pk_mul_f32 v[20:21], v[20:21], v[32:33] op_sel_hi:[1,0]
	v_add_f32_e32 v33, 1.0, v35
	v_pk_mul_f32 v[30:31], v[30:31], v[32:33] op_sel_hi:[1,0]
	v_rcp_f32_e32 v35, v33
	v_mul_f32_e32 v33, 0xbfb8aa3b, v30
	v_exp_f32_e32 v33, v33
	v_mul_f32_e32 v36, 0xbfb8aa3b, v31
	v_exp_f32_e32 v36, v36
	v_pk_mul_f32 v[28:29], v[28:29], v[34:35]
	v_add_f32_e32 v33, 1.0, v33
	v_rcp_f32_e32 v34, v33
	v_add_f32_e32 v33, 1.0, v36
	v_rcp_f32_e32 v35, v33
	v_pk_mul_f32 v[20:21], v[20:21], v[28:29]
	v_pk_mul_f32 v[22:23], v[22:23], v[32:33] op_sel_hi:[1,0]
	v_pk_mul_f32 v[24:25], v[24:25], v[32:33] op_sel_hi:[1,0]
	v_pk_mul_f32 v[28:29], v[30:31], v[34:35]
	v_cvt_pk_bf16_f32 v20, v20, v21
	v_pk_mul_f32 v[22:23], v[22:23], v[28:29]
	v_mul_f32_e32 v21, 0xbfb8aa3b, v24
	v_exp_f32_e32 v28, v21
	v_cvt_pk_bf16_f32 v21, v22, v23
	v_mul_f32_e32 v22, 0xbfb8aa3b, v25
	v_exp_f32_e32 v23, v22
	v_pk_mul_f32 v[26:27], v[26:27], v[32:33] op_sel_hi:[1,0]
	v_add_f32_e32 v22, 1.0, v28
	v_mul_f32_e32 v28, 0xbfb8aa3b, v26
	v_add_f32_e32 v23, 1.0, v23
	v_mul_f32_e32 v29, 0xbfb8aa3b, v27
	v_rcp_f32_e32 v22, v22
	v_rcp_f32_e32 v23, v23
	v_exp_f32_e32 v28, v28
	v_exp_f32_e32 v29, v29
	v_pk_mul_f32 v[16:17], v[16:17], v[32:33] op_sel_hi:[1,0]
	v_pk_mul_f32 v[22:23], v[24:25], v[22:23]
	v_add_f32_e32 v24, 1.0, v28
	v_add_f32_e32 v25, 1.0, v29
	v_rcp_f32_e32 v24, v24
	v_rcp_f32_e32 v25, v25
	v_pk_mul_f32 v[16:17], v[16:17], v[22:23]
	s_nop 0
	v_cvt_pk_bf16_f32 v22, v16, v17
	v_pk_mul_f32 v[16:17], v[18:19], v[32:33] op_sel_hi:[1,0]
	v_pk_mul_f32 v[18:19], v[26:27], v[24:25]
	s_nop 0
	v_pk_mul_f32 v[16:17], v[16:17], v[18:19]
	v_mad_i64_i32 v[18:19], s[26:27], v156, s43, v[142:143]
	v_cvt_pk_bf16_f32 v23, v16, v17
	v_fmamk_f32 v16, v145, 0x3a800000, v155
	v_rsq_f32_e32 v16, v16
	v_lshl_add_u64 v[18:19], v[18:19], 0, s[24:25]
	v_lshl_add_u64 v[18:19], v[18:19], 0, v[136:137]
	global_store_dwordx4 v[18:19], v[20:23], off
	v_pk_mul_f32 v[12:13], v[12:13], v[16:17] op_sel_hi:[1,0]
	s_nop 0
	v_mul_f32_e32 v17, 0xbfb8aa3b, v12
	v_exp_f32_e32 v17, v17
	v_mul_f32_e32 v18, 0xbfb8aa3b, v13
	v_exp_f32_e32 v19, v18
	v_add_f32_e32 v17, 1.0, v17
	v_rcp_f32_e32 v18, v17
	v_pk_mul_f32 v[4:5], v[4:5], v[16:17] op_sel_hi:[1,0]
	v_add_f32_e32 v17, 1.0, v19
	v_pk_mul_f32 v[14:15], v[14:15], v[16:17] op_sel_hi:[1,0]
	v_rcp_f32_e32 v19, v17
	v_mul_f32_e32 v17, 0xbfb8aa3b, v14
	v_exp_f32_e32 v17, v17
	v_mul_f32_e32 v20, 0xbfb8aa3b, v15
	v_exp_f32_e32 v20, v20
	v_pk_mul_f32 v[12:13], v[12:13], v[18:19]
	v_add_f32_e32 v17, 1.0, v17
	v_rcp_f32_e32 v18, v17
	v_add_f32_e32 v17, 1.0, v20
	v_rcp_f32_e32 v19, v17
	v_pk_mul_f32 v[4:5], v[4:5], v[12:13]
	v_pk_mul_f32 v[6:7], v[6:7], v[16:17] op_sel_hi:[1,0]
	v_pk_mul_f32 v[8:9], v[8:9], v[16:17] op_sel_hi:[1,0]
	v_pk_mul_f32 v[12:13], v[14:15], v[18:19]
	v_cvt_pk_bf16_f32 v4, v4, v5
	v_pk_mul_f32 v[6:7], v[6:7], v[12:13]
	v_mul_f32_e32 v5, 0xbfb8aa3b, v8
	v_exp_f32_e32 v12, v5
	v_cvt_pk_bf16_f32 v5, v6, v7
	v_mul_f32_e32 v6, 0xbfb8aa3b, v9
	v_exp_f32_e32 v7, v6
	v_pk_mul_f32 v[10:11], v[10:11], v[16:17] op_sel_hi:[1,0]
	v_add_f32_e32 v6, 1.0, v12
	v_mul_f32_e32 v12, 0xbfb8aa3b, v10
	v_add_f32_e32 v7, 1.0, v7
	v_mul_f32_e32 v13, 0xbfb8aa3b, v11
	v_rcp_f32_e32 v6, v6
	v_rcp_f32_e32 v7, v7
	v_exp_f32_e32 v12, v12
	v_exp_f32_e32 v13, v13
	v_pk_mul_f32 v[0:1], v[0:1], v[16:17] op_sel_hi:[1,0]
	v_pk_mul_f32 v[6:7], v[8:9], v[6:7]
	v_add_f32_e32 v8, 1.0, v12
	v_add_f32_e32 v9, 1.0, v13
	v_rcp_f32_e32 v8, v8
	v_rcp_f32_e32 v9, v9
	v_pk_mul_f32 v[0:1], v[0:1], v[6:7]
	s_nop 0
	v_cvt_pk_bf16_f32 v6, v0, v1
	v_pk_mul_f32 v[0:1], v[2:3], v[16:17] op_sel_hi:[1,0]
	v_pk_mul_f32 v[2:3], v[10:11], v[8:9]
	s_nop 0
	v_pk_mul_f32 v[0:1], v[0:1], v[2:3]
	s_nop 0
	v_cvt_pk_bf16_f32 v7, v0, v1
	v_mad_i64_i32 v[0:1], s[26:27], v147, s43, v[142:143]
	v_lshl_add_u64 v[0:1], v[0:1], 0, s[24:25]
	v_lshl_add_u64 v[0:1], v[0:1], 0, v[136:137]
	s_mov_b32 s25, s16
	s_mov_b32 s24, s18
	s_mov_b64 s[26:27], s[20:21]
	global_store_dwordx4 v[0:1], v[4:7], off
	s_cbranch_vccz .LBB0_1364
	s_waitcnt vmcnt(0)
	s_cmpk_gt_u32 s0, 0xff
	s_cbranch_scc1 .LBB0_1375
	s_barrier

; template <class Epi, class Sched>
; __device__ __forceinline__ void gemm_phase(LAS unsigned char* lds, const int K, const Sched& S, const Epi& E) {
;     ...
;         for (int a = 0; a < 2; ++a)
; #pragma unroll
;             for (int b = 0; b < 2; ++b)
; #pragma unroll
;                 for (int m = 0; m < 4; ++m)
; #pragma unroll
;                     for (int n = 0; n < 2; ++n) acc[a][b][m][n] = (f32x4){0.f, 0.f, 0.f, 0.f};
;         cur = nxt; cA = nA; cB = nB; ++ui;
.LBB0_1446:
	s_add_u32 s48, s14, 0x100
	v_mov_b32_e32 v0, 0
	s_addc_u32 s49, s15, 0
	s_mov_b32 s50, -2
	v_mov_b32_e32 v1, v0
	v_mov_b32_e32 v2, v0
	v_mov_b32_e32 v3, v0
	v_mov_b32_e32 v4, v0
	v_mov_b32_e32 v5, v0
	v_mov_b32_e32 v6, v0
	v_mov_b32_e32 v7, v0
	v_mov_b32_e32 v16, v0
	v_mov_b32_e32 v17, v0
	v_mov_b32_e32 v18, v0
	v_mov_b32_e32 v19, v0
	v_mov_b32_e32 v20, v0
	v_mov_b32_e32 v21, v0
	v_mov_b32_e32 v22, v0
	v_mov_b32_e32 v23, v0
	v_mov_b32_e32 v32, v0
	v_mov_b32_e32 v33, v0
	v_mov_b32_e32 v34, v0
	v_mov_b32_e32 v35, v0
	v_mov_b32_e32 v36, v0
	v_mov_b32_e32 v37, v0
	v_mov_b32_e32 v38, v0
	v_mov_b32_e32 v39, v0
	v_mov_b32_e32 v48, v0
	v_mov_b32_e32 v49, v0
	v_mov_b32_e32 v50, v0
	v_mov_b32_e32 v51, v0
	v_mov_b32_e32 v52, v0
	v_mov_b32_e32 v53, v0
	v_mov_b32_e32 v54, v0
	v_mov_b32_e32 v55, v0
	v_mov_b32_e32 v8, v0
	v_mov_b32_e32 v9, v0
	v_mov_b32_e32 v10, v0
	v_mov_b32_e32 v11, v0
	v_mov_b32_e32 v12, v0
	v_mov_b32_e32 v13, v0
	v_mov_b32_e32 v14, v0
	v_mov_b32_e32 v15, v0
	v_mov_b32_e32 v24, v0
	v_mov_b32_e32 v25, v0
	v_mov_b32_e32 v26, v0
	v_mov_b32_e32 v27, v0
	v_mov_b32_e32 v28, v0
	v_mov_b32_e32 v29, v0
	v_mov_b32_e32 v30, v0
	v_mov_b32_e32 v31, v0
	v_mov_b32_e32 v40, v0
	v_mov_b32_e32 v41, v0
	v_mov_b32_e32 v42, v0
	v_mov_b32_e32 v43, v0
	v_mov_b32_e32 v44, v0
	v_mov_b32_e32 v45, v0
	v_mov_b32_e32 v46, v0
	v_mov_b32_e32 v47, v0
	v_mov_b32_e32 v56, v0
	v_mov_b32_e32 v57, v0
	v_mov_b32_e32 v58, v0
	v_mov_b32_e32 v59, v0
	v_mov_b32_e32 v60, v0
	v_mov_b32_e32 v61, v0
	v_mov_b32_e32 v62, v0
	v_mov_b32_e32 v63, v0
	s_waitcnt vmcnt(16)
	v_mov_b32_e32 v64, v0
	v_mov_b32_e32 v65, v0
	v_mov_b32_e32 v66, v0
	v_mov_b32_e32 v67, v0
	v_mov_b32_e32 v68, v0
	v_mov_b32_e32 v69, v0
	v_mov_b32_e32 v70, v0
	v_mov_b32_e32 v71, v0
	v_mov_b32_e32 v80, v0
	v_mov_b32_e32 v81, v0
	v_mov_b32_e32 v82, v0
	v_mov_b32_e32 v83, v0
	v_mov_b32_e32 v84, v0
	v_mov_b32_e32 v85, v0
	v_mov_b32_e32 v86, v0
	v_mov_b32_e32 v87, v0
	v_mov_b32_e32 v96, v0
	v_mov_b32_e32 v97, v0
	v_mov_b32_e32 v98, v0
	v_mov_b32_e32 v99, v0
	v_mov_b32_e32 v100, v0
	v_mov_b32_e32 v101, v0
	v_mov_b32_e32 v102, v0
	v_mov_b32_e32 v103, v0
	v_mov_b32_e32 v112, v0
	v_mov_b32_e32 v113, v0
	v_mov_b32_e32 v114, v0
	v_mov_b32_e32 v115, v0
	v_mov_b32_e32 v116, v0
	v_mov_b32_e32 v117, v0
	v_mov_b32_e32 v118, v0
	v_mov_b32_e32 v119, v0
	v_mov_b32_e32 v72, v0
	v_mov_b32_e32 v73, v0
	v_mov_b32_e32 v74, v0
	v_mov_b32_e32 v75, v0
	v_mov_b32_e32 v76, v0
	v_mov_b32_e32 v77, v0
	v_mov_b32_e32 v78, v0
	v_mov_b32_e32 v79, v0
	v_mov_b32_e32 v88, v0
	v_mov_b32_e32 v89, v0
	v_mov_b32_e32 v90, v0
	v_mov_b32_e32 v91, v0
	v_mov_b32_e32 v92, v0
	v_mov_b32_e32 v93, v0
	v_mov_b32_e32 v94, v0
	v_mov_b32_e32 v95, v0
	v_mov_b32_e32 v104, v0
	v_mov_b32_e32 v105, v0
	v_mov_b32_e32 v106, v0
	v_mov_b32_e32 v107, v0
	v_mov_b32_e32 v108, v0
	v_mov_b32_e32 v109, v0
	v_mov_b32_e32 v110, v0
	v_mov_b32_e32 v111, v0
	v_mov_b32_e32 v120, v0
	v_mov_b32_e32 v121, v0
	v_mov_b32_e32 v122, v0
	v_mov_b32_e32 v123, v0
	v_mov_b32_e32 v124, v0
	v_mov_b32_e32 v125, v0
	v_mov_b32_e32 v126, v0
	v_mov_b32_e32 v127, v0
	s_cmpk_eq_i32 s47, 0x100
	s_cselect_b64 vcc, -1, 0

; __device__ __forceinline__ float bflo(unsigned u) { return __uint_as_float(u << 16); }
; __device__ __forceinline__ float bfhi(unsigned u) { return __uint_as_float(u & 0xffff0000u); }
;     __device__ __forceinline__ void operator()(Acc& acc, const Unit& u, int wr, int wc, int fr, int fq) const {
;     ...
;                 for (int m = 0; m < 4; ++m) { const int R = row0 + ai * 128 + m * 16;
;                     if (R < MP + MS) { float* ys = R < MP ? P.out + O_YP + (size_t)R * 1024 : P.out + O_YS + (size_t)(R - MP) * 1024;
; #pragma unroll
;                         for (int bj = 0; bj < 2; ++bj) { float* y = ys + u.pn * 256 + bj * 128 + cl0; const u32x4 v = xv[m][bj];
;                             *(f32x4*)y = (f32x4){bflo(v.x), bfhi(v.x), bflo(v.y), bfhi(v.y)} + acc[ai][bj][m][0]; *(f32x4*)(y + 4) = (f32x4){bflo(v.z), bfhi(v.z), bflo(v.w), bfhi(v.w)} + acc[ai][bj][m][1]; } } } }
.LBB0_1451:
	v_add_u32_e32 v96, 0xffff0020, v170
	v_cmp_gt_i32_e32 vcc, s30, v178
	v_mov_b32_e32 v173, v161
	s_waitcnt vmcnt(8)
	v_lshlrev_b32_e32 v100, 16, v141
	v_cndmask_b32_e32 v97, 0, v179, vcc
	v_cndmask_b32_e32 v96, v96, v178, vcc
	v_cndmask_b32_e64 v160, v186, 0, vcc
	v_lshl_add_u64 v[98:99], s[8:9], 0, v[160:161]
	v_lshlrev_b64 v[96:97], 12, v[96:97]
	v_lshl_add_u64 v[96:97], v[98:99], 0, v[96:97]
	v_lshl_add_u64 v[96:97], s[12:13], 2, v[96:97]
	v_lshlrev_b32_e32 v98, 16, v140
	v_and_b32_e32 v99, 0xffff0000, v140
	v_and_b32_e32 v101, 0xffff0000, v141
	v_lshl_add_u64 v[96:97], v[96:97], 0, v[172:173]
	v_pk_add_f32 v[94:95], v[94:95], v[100:101]
	v_pk_add_f32 v[92:93], v[92:93], v[98:99]
	global_store_dwordx4 v[96:97], v[92:95], off
	s_nop 1
	v_lshlrev_b32_e32 v92, 16, v142
	v_and_b32_e32 v93, 0xffff0000, v142
	v_lshlrev_b32_e32 v94, 16, v143
	v_and_b32_e32 v95, 0xffff0000, v143
	v_pk_add_f32 v[90:91], v[90:91], v[94:95]
	v_pk_add_f32 v[88:89], v[88:89], v[92:93]
	global_store_dwordx4 v[96:97], v[88:91], off offset:16
	s_nop 1
	v_lshlrev_b32_e32 v88, 16, v136
	v_and_b32_e32 v89, 0xffff0000, v136
	v_lshlrev_b32_e32 v90, 16, v137
	v_and_b32_e32 v91, 0xffff0000, v137
	v_pk_add_f32 v[86:87], v[86:87], v[90:91]
	v_pk_add_f32 v[84:85], v[84:85], v[88:89]
	global_store_dwordx4 v[96:97], v[84:87], off offset:512
	s_nop 1
	v_lshlrev_b32_e32 v84, 16, v138
	v_and_b32_e32 v85, 0xffff0000, v138
	v_lshlrev_b32_e32 v86, 16, v139
	v_and_b32_e32 v87, 0xffff0000, v139
	v_pk_add_f32 v[82:83], v[82:83], v[86:87]
	v_pk_add_f32 v[80:81], v[80:81], v[84:85]
	global_store_dwordx4 v[96:97], v[80:83], off offset:528
	s_or_b64 exec, exec, s[14:15]
	v_cmp_gt_i32_e32 vcc, s36, v176
	s_and_saveexec_b64 s[14:15], vcc
	s_cbranch_execnz .LBB0_1455
	s_branch .LBB0_1456

; __device__ __forceinline__ float bflo(unsigned u) { return __uint_as_float(u << 16); }
; __device__ __forceinline__ float bfhi(unsigned u) { return __uint_as_float(u & 0xffff0000u); }
;     __device__ __forceinline__ void operator()(Acc& acc, const Unit& u, int wr, int wc, int fr, int fq) const {
;     ...
;                 for (int m = 0; m < 4; ++m) { const int R = row0 + ai * 128 + m * 16;
;                     if (R < MP + MS) { float* ys = R < MP ? P.out + O_YP + (size_t)R * 1024 : P.out + O_YS + (size_t)(R - MP) * 1024;
; #pragma unroll
;                         for (int bj = 0; bj < 2; ++bj) { float* y = ys + u.pn * 256 + bj * 128 + cl0; const u32x4 v = xv[m][bj];
;                             *(f32x4*)y = (f32x4){bflo(v.x), bfhi(v.x), bflo(v.y), bfhi(v.y)} + acc[ai][bj][m][0]; *(f32x4*)(y + 4) = (f32x4){bflo(v.z), bfhi(v.z), bflo(v.w), bfhi(v.w)} + acc[ai][bj][m][1]; } } } }
.LBB0_1453:
	v_add_u32_e32 v112, 0xffff0010, v170
	v_cmp_gt_i32_e32 vcc, s30, v180
	v_mov_b32_e32 v173, v161
	s_waitcnt vmcnt(4)
	v_lshlrev_b32_e32 v116, 16, v149
	v_cndmask_b32_e32 v113, 0, v181, vcc
	v_cndmask_b32_e32 v112, v112, v180, vcc
	v_cndmask_b32_e64 v160, v186, 0, vcc
	v_lshl_add_u64 v[114:115], s[8:9], 0, v[160:161]
	v_lshlrev_b64 v[112:113], 12, v[112:113]
	v_lshl_add_u64 v[112:113], v[114:115], 0, v[112:113]
	v_lshl_add_u64 v[112:113], s[12:13], 2, v[112:113]
	v_lshlrev_b32_e32 v114, 16, v148
	v_and_b32_e32 v115, 0xffff0000, v148
	v_and_b32_e32 v117, 0xffff0000, v149
	v_lshl_add_u64 v[112:113], v[112:113], 0, v[172:173]
	v_pk_add_f32 v[110:111], v[110:111], v[116:117]
	v_pk_add_f32 v[108:109], v[108:109], v[114:115]
	global_store_dwordx4 v[112:113], v[108:111], off
	s_nop 1
	v_lshlrev_b32_e32 v108, 16, v150
	v_and_b32_e32 v109, 0xffff0000, v150
	v_lshlrev_b32_e32 v110, 16, v151
	v_and_b32_e32 v111, 0xffff0000, v151
	v_pk_add_f32 v[106:107], v[106:107], v[110:111]
	v_pk_add_f32 v[104:105], v[104:105], v[108:109]
	global_store_dwordx4 v[112:113], v[104:107], off offset:16
	s_nop 1
	v_lshlrev_b32_e32 v104, 16, v144
	v_and_b32_e32 v105, 0xffff0000, v144
	v_lshlrev_b32_e32 v106, 16, v145
	v_and_b32_e32 v107, 0xffff0000, v145
	v_pk_add_f32 v[102:103], v[102:103], v[106:107]
	v_pk_add_f32 v[100:101], v[100:101], v[104:105]
	global_store_dwordx4 v[112:113], v[100:103], off offset:512
	s_nop 1
	v_lshlrev_b32_e32 v100, 16, v146
	v_and_b32_e32 v101, 0xffff0000, v146
	v_lshlrev_b32_e32 v102, 16, v147
	v_and_b32_e32 v103, 0xffff0000, v147
	v_pk_add_f32 v[98:99], v[98:99], v[102:103]
	v_pk_add_f32 v[96:97], v[96:97], v[100:101]
	global_store_dwordx4 v[112:113], v[96:99], off offset:528
	s_or_b64 exec, exec, s[14:15]
	v_cmp_gt_i32_e32 vcc, s36, v178
	s_and_saveexec_b64 s[14:15], vcc
	s_cbranch_execnz .LBB0_1451

; __device__ __forceinline__ float bflo(unsigned u) { return __uint_as_float(u << 16); }
; __device__ __forceinline__ float bfhi(unsigned u) { return __uint_as_float(u & 0xffff0000u); }
;     __device__ __forceinline__ void operator()(Acc& acc, const Unit& u, int wr, int wc, int fr, int fq) const {
;     ...
;                 for (int m = 0; m < 4; ++m) { const int R = row0 + ai * 128 + m * 16;
;                     if (R < MP + MS) { float* ys = R < MP ? P.out + O_YP + (size_t)R * 1024 : P.out + O_YS + (size_t)(R - MP) * 1024;
; #pragma unroll
;                         for (int bj = 0; bj < 2; ++bj) { float* y = ys + u.pn * 256 + bj * 128 + cl0; const u32x4 v = xv[m][bj];
;                             *(f32x4*)y = (f32x4){bflo(v.x), bfhi(v.x), bflo(v.y), bfhi(v.y)} + acc[ai][bj][m][0]; *(f32x4*)(y + 4) = (f32x4){bflo(v.z), bfhi(v.z), bflo(v.w), bfhi(v.w)} + acc[ai][bj][m][1]; } } } }
.LBB0_1455:
	v_add_u32_e32 v80, 0xffff0030, v170
	v_cmp_gt_i32_e32 vcc, s30, v176
	v_mov_b32_e32 v173, v161
	s_waitcnt vmcnt(12)
	v_lshlrev_b32_e32 v84, 16, v133
	v_cndmask_b32_e32 v81, 0, v177, vcc
	v_cndmask_b32_e32 v80, v80, v176, vcc
	v_cndmask_b32_e64 v160, v186, 0, vcc
	v_lshl_add_u64 v[82:83], s[8:9], 0, v[160:161]
	v_lshlrev_b64 v[80:81], 12, v[80:81]
	v_lshl_add_u64 v[80:81], v[82:83], 0, v[80:81]
	v_lshl_add_u64 v[80:81], s[12:13], 2, v[80:81]
	v_lshlrev_b32_e32 v82, 16, v132
	v_and_b32_e32 v83, 0xffff0000, v132
	v_and_b32_e32 v85, 0xffff0000, v133
	v_lshl_add_u64 v[80:81], v[80:81], 0, v[172:173]
	v_pk_add_f32 v[78:79], v[78:79], v[84:85]
	v_pk_add_f32 v[76:77], v[76:77], v[82:83]
	global_store_dwordx4 v[80:81], v[76:79], off
	s_nop 1
	v_lshlrev_b32_e32 v76, 16, v134
	v_and_b32_e32 v77, 0xffff0000, v134
	v_lshlrev_b32_e32 v78, 16, v135
	v_and_b32_e32 v79, 0xffff0000, v135
	v_pk_add_f32 v[74:75], v[74:75], v[78:79]
	v_pk_add_f32 v[72:73], v[72:73], v[76:77]
	global_store_dwordx4 v[80:81], v[72:75], off offset:16
	s_nop 1
	v_lshlrev_b32_e32 v72, 16, v128
	v_and_b32_e32 v73, 0xffff0000, v128
	v_lshlrev_b32_e32 v74, 16, v129
	v_and_b32_e32 v75, 0xffff0000, v129
	v_pk_add_f32 v[70:71], v[70:71], v[74:75]
	v_pk_add_f32 v[68:69], v[68:69], v[72:73]
	global_store_dwordx4 v[80:81], v[68:71], off offset:512
	s_nop 1
	v_lshlrev_b32_e32 v68, 16, v130
	v_and_b32_e32 v69, 0xffff0000, v130
	v_lshlrev_b32_e32 v70, 16, v131
	v_and_b32_e32 v71, 0xffff0000, v131
	v_pk_add_f32 v[66:67], v[66:67], v[70:71]
	v_pk_add_f32 v[64:65], v[64:65], v[68:69]
	global_store_dwordx4 v[80:81], v[64:67], off offset:528

; __device__ __forceinline__ float bflo(unsigned u) { return __uint_as_float(u << 16); }
; __device__ __forceinline__ float bfhi(unsigned u) { return __uint_as_float(u & 0xffff0000u); }
;     __device__ __forceinline__ void operator()(Acc& acc, const Unit& u, int wr, int wc, int fr, int fq) const {
;     ...
;                 for (int m = 0; m < 4; ++m) { const int R = row0 + ai * 128 + m * 16;
;                     if (R < MP + MS) { float* ys = R < MP ? P.out + O_YP + (size_t)R * 1024 : P.out + O_YS + (size_t)(R - MP) * 1024;
; #pragma unroll
;                         for (int bj = 0; bj < 2; ++bj) { float* y = ys + u.pn * 256 + bj * 128 + cl0; const u32x4 v = xv[m][bj];
;                             *(f32x4*)y = (f32x4){bflo(v.x), bfhi(v.x), bflo(v.y), bfhi(v.y)} + acc[ai][bj][m][0]; *(f32x4*)(y + 4) = (f32x4){bflo(v.z), bfhi(v.z), bflo(v.w), bfhi(v.w)} + acc[ai][bj][m][1]; } } } }
.LBB0_1459:
	v_add_u32_e32 v32, 0xffff00a0, v170
	v_cmp_gt_i32_e32 vcc, s41, v170
	v_mov_b32_e32 v173, v161
	s_waitcnt vmcnt(8)
	v_lshlrev_b32_e32 v36, 16, v77
	v_cndmask_b32_e32 v33, 0, v91, vcc
	v_cndmask_b32_e32 v32, v32, v90, vcc
	v_cndmask_b32_e64 v160, v186, 0, vcc
	v_lshl_add_u64 v[34:35], s[8:9], 0, v[160:161]
	v_lshlrev_b64 v[32:33], 12, v[32:33]
	v_lshl_add_u64 v[32:33], v[34:35], 0, v[32:33]
	v_lshl_add_u64 v[32:33], s[12:13], 2, v[32:33]
	v_lshlrev_b32_e32 v34, 16, v76
	v_and_b32_e32 v35, 0xffff0000, v76
	v_and_b32_e32 v37, 0xffff0000, v77
	v_lshl_add_u64 v[32:33], v[32:33], 0, v[172:173]
	v_pk_add_f32 v[30:31], v[30:31], v[36:37]
	v_pk_add_f32 v[28:29], v[28:29], v[34:35]
	global_store_dwordx4 v[32:33], v[28:31], off
	s_nop 1
	v_lshlrev_b32_e32 v28, 16, v78
	v_and_b32_e32 v29, 0xffff0000, v78
	v_lshlrev_b32_e32 v30, 16, v79
	v_and_b32_e32 v31, 0xffff0000, v79
	v_pk_add_f32 v[26:27], v[26:27], v[30:31]
	v_pk_add_f32 v[24:25], v[24:25], v[28:29]
	global_store_dwordx4 v[32:33], v[24:27], off offset:16
	s_nop 1
	v_lshlrev_b32_e32 v24, 16, v72
	v_and_b32_e32 v25, 0xffff0000, v72
	v_lshlrev_b32_e32 v26, 16, v73
	v_and_b32_e32 v27, 0xffff0000, v73
	v_pk_add_f32 v[22:23], v[22:23], v[26:27]
	v_pk_add_f32 v[20:21], v[20:21], v[24:25]
	global_store_dwordx4 v[32:33], v[20:23], off offset:512
	s_nop 1
	v_lshlrev_b32_e32 v20, 16, v74
	v_and_b32_e32 v21, 0xffff0000, v74
	v_lshlrev_b32_e32 v22, 16, v75
	v_and_b32_e32 v23, 0xffff0000, v75
	v_pk_add_f32 v[18:19], v[18:19], v[22:23]
	v_pk_add_f32 v[16:17], v[16:17], v[20:21]
	global_store_dwordx4 v[32:33], v[16:19], off offset:528
	s_or_b64 exec, exec, s[14:15]
	v_cmp_gt_i32_e32 vcc, s42, v170
	s_and_saveexec_b64 s[14:15], vcc
	s_cbranch_execz .LBB0_1435
	s_branch .LBB0_1463

; __device__ __forceinline__ float bflo(unsigned u) { return __uint_as_float(u << 16); }
; __device__ __forceinline__ float bfhi(unsigned u) { return __uint_as_float(u & 0xffff0000u); }
;     __device__ __forceinline__ void operator()(Acc& acc, const Unit& u, int wr, int wc, int fr, int fq) const {
;     ...
;                 for (int m = 0; m < 4; ++m) { const int R = row0 + ai * 128 + m * 16;
;                     if (R < MP + MS) { float* ys = R < MP ? P.out + O_YP + (size_t)R * 1024 : P.out + O_YS + (size_t)(R - MP) * 1024;
; #pragma unroll
;                         for (int bj = 0; bj < 2; ++bj) { float* y = ys + u.pn * 256 + bj * 128 + cl0; const u32x4 v = xv[m][bj];
;                             *(f32x4*)y = (f32x4){bflo(v.x), bfhi(v.x), bflo(v.y), bfhi(v.y)} + acc[ai][bj][m][0]; *(f32x4*)(y + 4) = (f32x4){bflo(v.z), bfhi(v.z), bflo(v.w), bfhi(v.w)} + acc[ai][bj][m][1]; } } } }
.LBB0_1461:
	v_add_u32_e32 v48, 0xffff0090, v170
	v_cmp_gt_i32_e32 vcc, s39, v170
	v_mov_b32_e32 v173, v161
	s_waitcnt vmcnt(4)
	v_lshlrev_b32_e32 v52, 16, v85
	v_cndmask_b32_e32 v49, 0, v93, vcc
	v_cndmask_b32_e32 v48, v48, v92, vcc
	v_cndmask_b32_e64 v160, v186, 0, vcc
	v_lshl_add_u64 v[50:51], s[8:9], 0, v[160:161]
	v_lshlrev_b64 v[48:49], 12, v[48:49]
	v_lshl_add_u64 v[48:49], v[50:51], 0, v[48:49]
	v_lshl_add_u64 v[48:49], s[12:13], 2, v[48:49]
	v_lshlrev_b32_e32 v50, 16, v84
	v_and_b32_e32 v51, 0xffff0000, v84
	v_and_b32_e32 v53, 0xffff0000, v85
	v_lshl_add_u64 v[48:49], v[48:49], 0, v[172:173]
	v_pk_add_f32 v[46:47], v[46:47], v[52:53]
	v_pk_add_f32 v[44:45], v[44:45], v[50:51]
	global_store_dwordx4 v[48:49], v[44:47], off
	s_nop 1
	v_lshlrev_b32_e32 v44, 16, v86
	v_and_b32_e32 v45, 0xffff0000, v86
	v_lshlrev_b32_e32 v46, 16, v87
	v_and_b32_e32 v47, 0xffff0000, v87
	v_pk_add_f32 v[42:43], v[42:43], v[46:47]
	v_pk_add_f32 v[40:41], v[40:41], v[44:45]
	global_store_dwordx4 v[48:49], v[40:43], off offset:16
	s_nop 1
	v_lshlrev_b32_e32 v40, 16, v80
	v_and_b32_e32 v41, 0xffff0000, v80
	v_lshlrev_b32_e32 v42, 16, v81
	v_and_b32_e32 v43, 0xffff0000, v81
	v_pk_add_f32 v[38:39], v[38:39], v[42:43]
	v_pk_add_f32 v[36:37], v[36:37], v[40:41]
	global_store_dwordx4 v[48:49], v[36:39], off offset:512
	s_nop 1
	v_lshlrev_b32_e32 v36, 16, v82
	v_and_b32_e32 v37, 0xffff0000, v82
	v_lshlrev_b32_e32 v38, 16, v83
	v_and_b32_e32 v39, 0xffff0000, v83
	v_pk_add_f32 v[34:35], v[34:35], v[38:39]
	v_pk_add_f32 v[32:33], v[32:33], v[36:37]
	global_store_dwordx4 v[48:49], v[32:35], off offset:528
	s_or_b64 exec, exec, s[14:15]
	v_cmp_gt_i32_e32 vcc, s40, v170
	s_and_saveexec_b64 s[14:15], vcc
	s_cbranch_execnz .LBB0_1459

; __device__ __forceinline__ float bflo(unsigned u) { return __uint_as_float(u << 16); }
; __device__ __forceinline__ float bfhi(unsigned u) { return __uint_as_float(u & 0xffff0000u); }
;     __device__ __forceinline__ void operator()(Acc& acc, const Unit& u, int wr, int wc, int fr, int fq) const {
;     ...
;                 for (int m = 0; m < 4; ++m) { const int R = row0 + ai * 128 + m * 16;
;                     if (R < MP + MS) { float* ys = R < MP ? P.out + O_YP + (size_t)R * 1024 : P.out + O_YS + (size_t)(R - MP) * 1024;
; #pragma unroll
;                         for (int bj = 0; bj < 2; ++bj) { float* y = ys + u.pn * 256 + bj * 128 + cl0; const u32x4 v = xv[m][bj];
;                             *(f32x4*)y = (f32x4){bflo(v.x), bfhi(v.x), bflo(v.y), bfhi(v.y)} + acc[ai][bj][m][0]; *(f32x4*)(y + 4) = (f32x4){bflo(v.z), bfhi(v.z), bflo(v.w), bfhi(v.w)} + acc[ai][bj][m][1]; } } } }
.LBB0_1463:
	v_add_u32_e32 v16, 0xffff00b0, v170
	v_cmp_gt_i32_e32 vcc, s43, v170
	v_mov_b32_e32 v173, v161
	s_waitcnt vmcnt(12)
	v_lshlrev_b32_e32 v20, 16, v69
	v_cndmask_b32_e32 v17, 0, v89, vcc
	v_cndmask_b32_e32 v16, v16, v88, vcc
	v_cndmask_b32_e64 v160, v186, 0, vcc
	v_lshl_add_u64 v[18:19], s[8:9], 0, v[160:161]
	v_lshlrev_b64 v[16:17], 12, v[16:17]
	v_lshl_add_u64 v[16:17], v[18:19], 0, v[16:17]
	v_lshl_add_u64 v[16:17], s[12:13], 2, v[16:17]
	v_lshlrev_b32_e32 v18, 16, v68
	v_and_b32_e32 v19, 0xffff0000, v68
	v_and_b32_e32 v21, 0xffff0000, v69
	v_lshl_add_u64 v[16:17], v[16:17], 0, v[172:173]
	v_pk_add_f32 v[14:15], v[14:15], v[20:21]
	v_pk_add_f32 v[12:13], v[12:13], v[18:19]
	global_store_dwordx4 v[16:17], v[12:15], off
	s_nop 1
	v_lshlrev_b32_e32 v12, 16, v70
	v_and_b32_e32 v13, 0xffff0000, v70
	v_lshlrev_b32_e32 v14, 16, v71
	v_and_b32_e32 v15, 0xffff0000, v71
	v_pk_add_f32 v[10:11], v[10:11], v[14:15]
	v_pk_add_f32 v[8:9], v[8:9], v[12:13]
	global_store_dwordx4 v[16:17], v[8:11], off offset:16
	s_nop 1
	v_lshlrev_b32_e32 v8, 16, v64
	v_and_b32_e32 v9, 0xffff0000, v64
	v_lshlrev_b32_e32 v10, 16, v65
	v_and_b32_e32 v11, 0xffff0000, v65
	v_pk_add_f32 v[6:7], v[6:7], v[10:11]
	v_pk_add_f32 v[4:5], v[4:5], v[8:9]
	global_store_dwordx4 v[16:17], v[4:7], off offset:512
	s_nop 1
	v_lshlrev_b32_e32 v4, 16, v66
	v_and_b32_e32 v5, 0xffff0000, v66
	v_lshlrev_b32_e32 v6, 16, v67
	v_and_b32_e32 v7, 0xffff0000, v67
	v_pk_add_f32 v[2:3], v[2:3], v[6:7]
	v_pk_add_f32 v[0:1], v[0:1], v[4:5]
	global_store_dwordx4 v[16:17], v[0:3], off offset:528
	s_branch .LBB0_1435
